# compress w1 weights K32-blocked too; GEMM loop: s_setprio 1 for the post-barrier half, DMA issue moved to the tail of the MFMA block
# speedup vs baseline: 1.1432x; 1.0193x over previous
; DI unsigned pk2(float lo, float hi) { f32x2 v = {lo, hi}; bf16x2_t r = __builtin_convertvector(v, bf16x2_t); return __builtin_bit_cast(unsigned, r); }
; DI void cvt_job(const float* src, bf16_t* dst, int K, int Nn, int NnPad, int remap, char* smem) {
;     ...
;         {
;             const int nl = tid >> 2, part = tid & 3;
;             u32x4 v0, v1;
; #pragma unroll
;             for (int j = 0; j < 4; ++j) {
;                 v0[j] = pk2(tile[(part * 16 + 2 * j) * 65 + nl], tile[(part * 16 + 2 * j + 1) * 65 + nl]);
;                 v1[j] = pk2(tile[(part * 16 + 8 + 2 * j) * 65 + nl], tile[(part * 16 + 8 + 2 * j + 1) * 65 + nl]);
;             }
;             bf16_t* d = dst + (size_t)(nt * 64 + nl) * K + kt * 64 + part * 16;
;             *(u32x4*)d = v0; *(u32x4*)(d + 8) = v1;
;         }
.LBB0_103:
	s_or_b64 exec, exec, s[24:25]
	s_waitcnt vmcnt(1)
	ds_write_b32 v12, v2 offset:14560
	s_waitcnt vmcnt(0)
	ds_write_b32 v12, v5 offset:15600
	v_add_u32_e32 v2, 0x800, v11
	s_waitcnt lgkmcnt(0)
	s_barrier
	ds_read2_b32 v[6:7], v10 offset1:130
	ds_read2_b32 v[14:15], v11 offset0:65 offset1:195
	ds_read2_b32 v[16:17], v2 offset0:8 offset1:73
	s_add_i32 s24, s34, s37
	s_ashr_i32 s25, s24, 31
	v_mov_b32_e32 v5, v3
	s_waitcnt lgkmcnt(1)
	v_cvt_pk_bf16_f32 v14, v6, v14
	s_waitcnt lgkmcnt(0)
	v_cvt_pk_bf16_f32 v18, v16, v17
	ds_read2_b32 v[16:17], v2 offset0:138 offset1:203
	v_add_u32_e32 v2, 0x400, v10
	ds_read2_b32 v[20:21], v2 offset0:4 offset1:134
	v_add_u32_e32 v2, 0x400, v11
	ds_read2_b32 v[22:23], v2 offset0:69 offset1:199
	v_add_u32_e32 v2, 0xc00, v11
	v_cvt_pk_bf16_f32 v15, v7, v15
	ds_read2_b32 v[6:7], v2 offset0:142 offset1:207
	s_waitcnt lgkmcnt(3)
	v_cvt_pk_bf16_f32 v19, v16, v17
	s_waitcnt lgkmcnt(1)
	v_cvt_pk_bf16_f32 v17, v21, v23
	ds_read2_b32 v[24:25], v2 offset0:12 offset1:77
	s_add_i32 s35, s35, s31
	s_waitcnt lgkmcnt(1)
	v_cvt_pk_bf16_f32 v21, v6, v7
	v_add_u32_e32 v6, s36, v9
	v_ashrrev_i32_e32 v7, 31, v6
	v_lshlrev_b64 v[6:7], 6, v[6:7]
	v_lshl_add_u64 v[6:7], s[22:23], 0, v[6:7]
	s_mul_i32 s98, s24, 0x200
	s_mov_b32 s99, 0
	v_lshl_add_u64 v[6:7], s[98:99], 0, v[6:7]
	s_add_i32 s34, s34, s33
	v_cvt_pk_bf16_f32 v16, v20, v22
	v_lshrrev_b32_e32 v254, 6, v4
	v_mul_u32_u24_e32 v254, 0x4000, v254
	v_and_or_b32 v254, v4, 32, v254
	v_mov_b32_e32 v255, 0
	v_lshl_add_u64 v[6:7], v[6:7], 0, v[254:255]
	s_cmpk_lt_i32 s35, 0x80
	s_waitcnt lgkmcnt(0)
	v_cvt_pk_bf16_f32 v20, v24, v25
	global_store_dwordx4 v[6:7], v[14:17], off
	global_store_dwordx4 v[6:7], v[18:21], off offset:16
	s_barrier
	s_cbranch_scc0 .LBB0_120

; DI f32x4 mfma(bf16x8 a, bf16x8 b, f32x4 c) { return __builtin_amdgcn_mfma_f32_16x16x32_bf16(a, b, c, 0, 0, 0); }
; #define G_LOAD(PA, PB, STEP) do { _Pragma("unroll") for (int i_ = 0; i_ < 2; ++i_) ra[i_] = *(const u32x4*)((PA) + (size_t)(64 * i_) * K + (STEP) * 32); \
;         _Pragma("unroll") for (int i_ = 0; i_ < 4; ++i_) rb[i_] = *(const u32x4*)((PB) + (size_t)(64 * i_) * K + (STEP) * 32); } while (0)
; #define G_STORE(BUF) do { _Pragma("unroll") for (int i_ = 0; i_ < 2; ++i_) *(u32x4*)(sA + (BUF) * 128 * 40 + (lrow + 64 * i_) * 40 + lcc * 8) = ra[i_]; \
;         _Pragma("unroll") for (int i_ = 0; i_ < 4; ++i_) *(u32x4*)(sB + (BUF) * 256 * 40 + (lrow + 64 * i_) * 40 + lcc * 8) = rb[i_]; } while (0)
; template <int EPI> ...
;     ...
;         for (int kt = 0; kt < nk; ++kt) {
;             const int buf = kt & 1;
;             const bf16_t* a_ = sA + buf * 128 * 40 + (wr * 64 + fr) * 40 + fq * 8;
;             const bf16_t* b_ = sB + buf * 256 * 40 + (wc * 128 + fr) * 40 + fq * 8;
;             bf16x8 af[4];
; #pragma unroll
;             for (int i = 0; i < 4; ++i) af[i] = *(const bf16x8*)(a_ + i * 16 * 40);
; #pragma unroll
;             for (int jh = 0; jh < 2; ++jh) {
;                 bf16x8 bfr[4];
; #pragma unroll
;                 for (int j = 0; j < 4; ++j) bfr[j] = *(const bf16x8*)(b_ + (jh * 4 + j) * 16 * 40);
; #pragma unroll
;                 for (int i = 0; i < 4; ++i)
; #pragma unroll
;                     for (int j = 0; j < 4; ++j) acc[i][jh * 4 + j] = mfma(bfr[j], af[i], acc[i][jh * 4 + j]);
;             }
;             G_STORE(buf ^ 1);
;             {
;                 const bool cur = kt + 2 < nk;
;                 const bf16_t* pa = cur ? Ag : An; const bf16_t* pb = cur ? Bg : Bn;
;                 const int st = cur ? kt + 2 : kt + 2 - nk;
;                 G_LOAD(pa, pb, st);
;             }
;             __syncthreads();
;         }
.Lg162_top:
	s_setprio 0
	s_waitcnt lgkmcnt(4)
	v_mfma_f32_16x16x32_bf16 v[148:151], v[160:163], v[10:13], v[148:151]
	v_mfma_f32_16x16x32_bf16 v[116:119], v[160:163], v[14:17], v[116:119]
	v_mfma_f32_16x16x32_bf16 v[84:87], v[160:163], v[18:21], v[84:87]
	v_mfma_f32_16x16x32_bf16 v[52:55], v[160:163], v[152:155], v[52:55]
	v_mfma_f32_16x16x32_bf16 v[144:147], v[174:177], v[10:13], v[144:147]
	v_mfma_f32_16x16x32_bf16 v[112:115], v[174:177], v[14:17], v[112:115]
	v_mfma_f32_16x16x32_bf16 v[80:83], v[174:177], v[18:21], v[80:83]
	v_mfma_f32_16x16x32_bf16 v[48:51], v[174:177], v[152:155], v[48:51]
	v_mfma_f32_16x16x32_bf16 v[140:143], v[178:181], v[10:13], v[140:143]
	v_mfma_f32_16x16x32_bf16 v[108:111], v[178:181], v[14:17], v[108:111]
	v_mfma_f32_16x16x32_bf16 v[76:79], v[178:181], v[18:21], v[76:79]
	v_mfma_f32_16x16x32_bf16 v[44:47], v[178:181], v[152:155], v[44:47]
	v_mfma_f32_16x16x32_bf16 v[136:139], v[182:185], v[10:13], v[136:139]
	v_mfma_f32_16x16x32_bf16 v[104:107], v[182:185], v[14:17], v[104:107]
	v_mfma_f32_16x16x32_bf16 v[72:75], v[182:185], v[18:21], v[72:75]
	v_mfma_f32_16x16x32_bf16 v[40:43], v[182:185], v[152:155], v[40:43]
	s_waitcnt vmcnt(6)
	s_waitcnt lgkmcnt(0)
	s_barrier
	s_add_u32 s13, s9, 0x6000
	s_cmp_eq_u32 s13, 0x12000
	s_cselect_b32 s13, 0, s13
	v_add_u32_e32 v8, s13, v6
	v_add_u32_e32 v9, s13, v7
	ds_read_b128 v[160:163], v9
	ds_read_b128 v[174:177], v9 offset:1024
	ds_read_b128 v[178:181], v9 offset:2048
	ds_read_b128 v[182:185], v9 offset:3072
	s_cmp_eq_u32 s4, 29
	s_cbranch_scc1 .Lg162_sw
.Lg162_swret:
	s_add_u32 m0, s9, s12
	s_setprio 1
	v_mfma_f32_16x16x32_bf16 v[132:135], v[192:195], v[10:13], v[132:135]
	v_mfma_f32_16x16x32_bf16 v[128:131], v[196:199], v[10:13], v[128:131]
	v_mfma_f32_16x16x32_bf16 v[124:127], v[200:203], v[10:13], v[124:127]
	v_mfma_f32_16x16x32_bf16 v[120:123], v[204:207], v[10:13], v[120:123]
	ds_read_b128 v[10:13], v8
	v_mfma_f32_16x16x32_bf16 v[100:103], v[192:195], v[14:17], v[100:103]
	v_mfma_f32_16x16x32_bf16 v[96:99], v[196:199], v[14:17], v[96:99]
	v_mfma_f32_16x16x32_bf16 v[92:95], v[200:203], v[14:17], v[92:95]
	v_mfma_f32_16x16x32_bf16 v[88:91], v[204:207], v[14:17], v[88:91]
	ds_read_b128 v[14:17], v8 offset:1024
	v_mfma_f32_16x16x32_bf16 v[68:71], v[192:195], v[18:21], v[68:71]
	global_load_lds_dwordx4 v0, s[98:99]
	v_mfma_f32_16x16x32_bf16 v[64:67], v[196:199], v[18:21], v[64:67]
	global_load_lds_dwordx4 v1, s[98:99] offset:1024
	v_mfma_f32_16x16x32_bf16 v[60:63], v[200:203], v[18:21], v[60:63]
	global_load_lds_dwordx4 v2, s[100:101] offset:2048
	v_mfma_f32_16x16x32_bf16 v[56:59], v[204:207], v[18:21], v[56:59]
	global_load_lds_dwordx4 v3, s[100:101] offset:3072
	ds_read_b128 v[18:21], v8 offset:6144
	v_mfma_f32_16x16x32_bf16 v[36:39], v[192:195], v[152:155], v[36:39]
	s_add_u32 m0, m0, 0x1000
	v_mfma_f32_16x16x32_bf16 v[32:35], v[196:199], v[152:155], v[32:35]
	global_load_lds_dwordx4 v4, s[100:101]
	v_mfma_f32_16x16x32_bf16 v[28:31], v[200:203], v[152:155], v[28:31]
	global_load_lds_dwordx4 v5, s[100:101] offset:1024
	v_mfma_f32_16x16x32_bf16 v[24:27], v[204:207], v[152:155], v[24:27]
	ds_read_b128 v[152:155], v8 offset:7168
	ds_read_b128 v[192:195], v9 offset:6144
	ds_read_b128 v[196:199], v9 offset:7168
	ds_read_b128 v[200:203], v9 offset:8192
	ds_read_b128 v[204:207], v9 offset:9216
	s_add_u32 s98, s98, 0x200000
	s_addc_u32 s99, s99, 0
	s_add_u32 s100, s100, 0x30000
	s_addc_u32 s101, s101, 0
	s_add_u32 s9, s9, 0x6000
	s_cmp_eq_u32 s9, 0x12000
	s_cselect_b32 s9, 0, s9
	s_add_u32 s4, s4, 1
	s_cmp_lt_u32 s4, 31
	s_cbranch_scc1 .Lg162_top
	s_setprio 0
	s_waitcnt lgkmcnt(4)
	v_mfma_f32_16x16x32_bf16 v[148:151], v[160:163], v[10:13], v[148:151]
	v_mfma_f32_16x16x32_bf16 v[116:119], v[160:163], v[14:17], v[116:119]
	v_mfma_f32_16x16x32_bf16 v[84:87], v[160:163], v[18:21], v[84:87]
	v_mfma_f32_16x16x32_bf16 v[52:55], v[160:163], v[152:155], v[52:55]
	v_mfma_f32_16x16x32_bf16 v[144:147], v[174:177], v[10:13], v[144:147]
	v_mfma_f32_16x16x32_bf16 v[112:115], v[174:177], v[14:17], v[112:115]
	v_mfma_f32_16x16x32_bf16 v[80:83], v[174:177], v[18:21], v[80:83]
	v_mfma_f32_16x16x32_bf16 v[48:51], v[174:177], v[152:155], v[48:51]
	v_mfma_f32_16x16x32_bf16 v[140:143], v[178:181], v[10:13], v[140:143]
	v_mfma_f32_16x16x32_bf16 v[108:111], v[178:181], v[14:17], v[108:111]
	v_mfma_f32_16x16x32_bf16 v[76:79], v[178:181], v[18:21], v[76:79]
	v_mfma_f32_16x16x32_bf16 v[44:47], v[178:181], v[152:155], v[44:47]
	v_mfma_f32_16x16x32_bf16 v[136:139], v[182:185], v[10:13], v[136:139]
	v_mfma_f32_16x16x32_bf16 v[104:107], v[182:185], v[14:17], v[104:107]
	v_mfma_f32_16x16x32_bf16 v[72:75], v[182:185], v[18:21], v[72:75]
	v_mfma_f32_16x16x32_bf16 v[40:43], v[182:185], v[152:155], v[40:43]
	s_waitcnt vmcnt(6)
	s_waitcnt lgkmcnt(0)
	s_barrier
	s_add_u32 m0, s9, s12
	s_setprio 1
	v_mfma_f32_16x16x32_bf16 v[132:135], v[192:195], v[10:13], v[132:135]
	v_mfma_f32_16x16x32_bf16 v[128:131], v[196:199], v[10:13], v[128:131]
	v_mfma_f32_16x16x32_bf16 v[124:127], v[200:203], v[10:13], v[124:127]
	v_mfma_f32_16x16x32_bf16 v[120:123], v[204:207], v[10:13], v[120:123]
	v_mfma_f32_16x16x32_bf16 v[100:103], v[192:195], v[14:17], v[100:103]
	v_mfma_f32_16x16x32_bf16 v[96:99], v[196:199], v[14:17], v[96:99]
	v_mfma_f32_16x16x32_bf16 v[92:95], v[200:203], v[14:17], v[92:95]
	v_mfma_f32_16x16x32_bf16 v[88:91], v[204:207], v[14:17], v[88:91]
	v_mfma_f32_16x16x32_bf16 v[68:71], v[192:195], v[18:21], v[68:71]
	global_load_lds_dwordx4 v0, s[98:99]
	v_mfma_f32_16x16x32_bf16 v[64:67], v[196:199], v[18:21], v[64:67]
	global_load_lds_dwordx4 v1, s[98:99] offset:1024
	v_mfma_f32_16x16x32_bf16 v[60:63], v[200:203], v[18:21], v[60:63]
	global_load_lds_dwordx4 v2, s[100:101] offset:2048
	v_mfma_f32_16x16x32_bf16 v[56:59], v[204:207], v[18:21], v[56:59]
	global_load_lds_dwordx4 v3, s[100:101] offset:3072
	v_mfma_f32_16x16x32_bf16 v[36:39], v[192:195], v[152:155], v[36:39]
	s_add_u32 m0, m0, 0x1000
	v_mfma_f32_16x16x32_bf16 v[32:35], v[196:199], v[152:155], v[32:35]
	global_load_lds_dwordx4 v4, s[100:101]
	v_mfma_f32_16x16x32_bf16 v[28:31], v[200:203], v[152:155], v[28:31]
	global_load_lds_dwordx4 v5, s[100:101] offset:1024
	v_mfma_f32_16x16x32_bf16 v[24:27], v[204:207], v[152:155], v[24:27]
	s_add_u32 s98, s98, 0x200000
	s_addc_u32 s99, s99, 0
	s_add_u32 s100, s100, 0x30000
	s_addc_u32 s101, s101, 0
	s_add_u32 s9, s9, 0x6000
	s_cmp_eq_u32 s9, 0x12000
	s_cselect_b32 s9, 0, s9
	s_add_u32 s4, s4, 1
	s_branch .Lg162_end

; DI unsigned pk2(float lo, float hi) { f32x2 v = {lo, hi}; bf16x2_t r = __builtin_convertvector(v, bf16x2_t); return __builtin_bit_cast(unsigned, r); }
; DI f32x4 mfma(bf16x8 a, bf16x8 b, f32x4 c) { return __builtin_amdgcn_mfma_f32_16x16x32_bf16(a, b, c, 0, 0, 0); }
; DI void phase_compress(const Params& p, int l, char* smem) {
;     ...
; #pragma unroll 4
;         for (int ks = 0; ks < 64; ++ks) {
;             const int t = ks >> 1, db = (ks & 1) * 32 + fq * 8;
;             const u32x4 xv = *(const u32x4*)(xr + (size_t)t * DINP + db);
;             const f32x4 p0 = *(const f32x4*)(pos + t * 64 + db), p1 = *(const f32x4*)(pos + t * 64 + db + 4);
;             bf16x8 wf[4];
; #pragma unroll
;             for (int i = 0; i < 4; ++i) wf[i] = *(const bf16x8*)(w1 + (size_t)i * 16 * 2048 + ks * 32);
;             u32x4 xb;
;             xb[0] = pk2(__uint_as_float(xv[0] << 16) + p0[0], __uint_as_float(xv[0] & 0xffff0000u) + p0[1]);
;             xb[1] = pk2(__uint_as_float(xv[1] << 16) + p0[2], __uint_as_float(xv[1] & 0xffff0000u) + p0[3]);
;             xb[2] = pk2(__uint_as_float(xv[2] << 16) + p1[0], __uint_as_float(xv[2] & 0xffff0000u) + p1[1]);
;             xb[3] = pk2(__uint_as_float(xv[3] << 16) + p1[2], __uint_as_float(xv[3] & 0xffff0000u) + p1[3]);
;             const bf16x8 bx = __builtin_bit_cast(bf16x8, xb);
; #pragma unroll
;             for (int i = 0; i < 4; ++i) acc[i] = mfma(wf[i], bx, acc[i]);
;         }
.LBB0_357:
	v_lshl_add_u64 v[20:21], v[68:69], 0, v[46:47]
	s_mov_b64 s[24:25], 0x2000
	v_lshl_add_u64 v[28:29], v[70:71], 0, v[46:47]
	v_and_b32_e32 v4, 0xcf, v210
	v_mul_u32_u24_e32 v4, 0xfc0, v4
	v_sub_co_u32_e32 v28, vcc, v28, v4
	s_nop 1
	v_subbrev_co_u32_e32 v29, vcc, 0, v29, vcc
	v_lshl_add_u64 v[36:37], v[66:67], 0, s[14:15]
	v_lshl_add_u64 v[22:23], v[20:21], 0, s[24:25]
	s_mov_b64 s[24:25], 0x4000
	v_lshl_add_u64 v[30:31], v[28:29], 0, s[24:25]
	v_lshl_add_u64 v[32:33], v[30:31], 0, s[24:25]
	v_lshl_add_u64 v[34:35], v[32:33], 0, s[24:25]
	global_load_dwordx4 v[24:27], v[20:21], off offset:3968
	global_load_dwordx4 v[38:41], v[36:37], off offset:16
	global_load_dwordx4 v[76:79], v[36:37], off
	global_load_dwordx4 v[80:83], v[28:29], off
	global_load_dwordx4 v[84:87], v[28:29], off offset:1024
	global_load_dwordx4 v[88:91], v[28:29], off offset:2048
	global_load_dwordx4 v[92:95], v[28:29], off offset:3072
	global_load_dwordx4 v[96:99], v[20:21], off offset:4032
	global_load_dwordx4 v[104:107], v[36:37], off offset:144
	global_load_dwordx4 v[100:103], v[36:37], off offset:128
	global_load_dwordx4 v[108:111], v[30:31], off
	global_load_dwordx4 v[112:115], v[30:31], off offset:1024
	global_load_dwordx4 v[116:119], v[30:31], off offset:2048
	global_load_dwordx4 v[120:123], v[30:31], off offset:3072
	global_load_dwordx4 v[124:127], v[22:23], off offset:1920
	global_load_dwordx4 v[132:135], v[36:37], off offset:272
	global_load_dwordx4 v[128:131], v[36:37], off offset:256
	global_load_dwordx4 v[136:139], v[32:33], off
	global_load_dwordx4 v[140:143], v[32:33], off offset:1024
	global_load_dwordx4 v[144:147], v[32:33], off offset:2048
	global_load_dwordx4 v[148:151], v[32:33], off offset:3072
	global_load_dwordx4 v[152:155], v[22:23], off offset:1984
	global_load_dwordx4 v[160:163], v[36:37], off offset:400
	global_load_dwordx4 v[156:159], v[36:37], off offset:384
	global_load_dwordx4 v[164:167], v[34:35], off
	global_load_dwordx4 v[168:171], v[34:35], off offset:1024
	global_load_dwordx4 v[172:175], v[34:35], off offset:2048
	global_load_dwordx4 v[176:179], v[34:35], off offset:3072
	s_mov_b64 s[24:25], 0x3000
	v_lshl_add_u64 v[20:21], v[20:21], 0, s[24:25]
	v_lshl_add_u64 v[22:23], v[22:23], 0, s[24:25]
	s_mov_b64 s[24:25], 0x10000
	v_lshl_add_u64 v[28:29], v[28:29], 0, s[24:25]
	v_lshl_add_u64 v[30:31], v[30:31], 0, s[24:25]
	v_lshl_add_u64 v[32:33], v[32:33], 0, s[24:25]
	v_lshl_add_u64 v[34:35], v[34:35], 0, s[24:25]
	s_mov_b64 s[24:25], 0x200
	v_lshl_add_u64 v[36:37], v[36:37], 0, s[24:25]
	s_mov_b32 s14, 0
.Lcmp_loop:
	s_waitcnt vmcnt(21)
	v_lshlrev_b32_e32 v4, 16, v24
	v_and_b32_e32 v5, 0xffff0000, v24
	v_pk_add_f32 v[4:5], v[76:77], v[4:5]
	s_nop 0
	v_cvt_pk_bf16_f32 v24, v4, v5
	v_lshlrev_b32_e32 v6, 16, v25
	v_and_b32_e32 v7, 0xffff0000, v25
	v_pk_add_f32 v[6:7], v[78:79], v[6:7]
	s_nop 0
	v_cvt_pk_bf16_f32 v25, v6, v7
	v_lshlrev_b32_e32 v4, 16, v26
	v_and_b32_e32 v5, 0xffff0000, v26
	v_pk_add_f32 v[4:5], v[38:39], v[4:5]
	s_nop 0
	v_cvt_pk_bf16_f32 v26, v4, v5
	v_lshlrev_b32_e32 v6, 16, v27
	v_and_b32_e32 v7, 0xffff0000, v27
	v_pk_add_f32 v[6:7], v[40:41], v[6:7]
	s_nop 0
	v_cvt_pk_bf16_f32 v27, v6, v7
	s_nop 1
	v_mfma_f32_16x16x32_bf16 v[16:19], v[80:83], v[24:27], v[16:19]
	v_mfma_f32_16x16x32_bf16 v[0:3], v[84:87], v[24:27], v[0:3]
	v_mfma_f32_16x16x32_bf16 v[12:15], v[88:91], v[24:27], v[12:15]
	v_mfma_f32_16x16x32_bf16 v[8:11], v[92:95], v[24:27], v[8:11]
	global_load_dwordx4 v[24:27], v[20:21], off offset:3968
	global_load_dwordx4 v[38:41], v[36:37], off offset:16
	global_load_dwordx4 v[76:79], v[36:37], off
	global_load_dwordx4 v[80:83], v[28:29], off
	global_load_dwordx4 v[84:87], v[28:29], off offset:1024
	global_load_dwordx4 v[88:91], v[28:29], off offset:2048
	global_load_dwordx4 v[92:95], v[28:29], off offset:3072
	s_waitcnt vmcnt(21)
	v_lshlrev_b32_e32 v4, 16, v96
	v_and_b32_e32 v5, 0xffff0000, v96
	v_pk_add_f32 v[4:5], v[100:101], v[4:5]
	s_nop 0
	v_cvt_pk_bf16_f32 v96, v4, v5
	v_lshlrev_b32_e32 v6, 16, v97
	v_and_b32_e32 v7, 0xffff0000, v97
	v_pk_add_f32 v[6:7], v[102:103], v[6:7]
	s_nop 0
	v_cvt_pk_bf16_f32 v97, v6, v7
	v_lshlrev_b32_e32 v4, 16, v98
	v_and_b32_e32 v5, 0xffff0000, v98
	v_pk_add_f32 v[4:5], v[104:105], v[4:5]
	s_nop 0
	v_cvt_pk_bf16_f32 v98, v4, v5
	v_lshlrev_b32_e32 v6, 16, v99
	v_and_b32_e32 v7, 0xffff0000, v99
	v_pk_add_f32 v[6:7], v[106:107], v[6:7]
	s_nop 0
	v_cvt_pk_bf16_f32 v99, v6, v7
	s_nop 1
	v_mfma_f32_16x16x32_bf16 v[16:19], v[108:111], v[96:99], v[16:19]
	v_mfma_f32_16x16x32_bf16 v[0:3], v[112:115], v[96:99], v[0:3]
	v_mfma_f32_16x16x32_bf16 v[12:15], v[116:119], v[96:99], v[12:15]
	v_mfma_f32_16x16x32_bf16 v[8:11], v[120:123], v[96:99], v[8:11]
	global_load_dwordx4 v[96:99], v[20:21], off offset:4032
	global_load_dwordx4 v[104:107], v[36:37], off offset:144
	global_load_dwordx4 v[100:103], v[36:37], off offset:128
	global_load_dwordx4 v[108:111], v[30:31], off
	global_load_dwordx4 v[112:115], v[30:31], off offset:1024
	global_load_dwordx4 v[116:119], v[30:31], off offset:2048
	global_load_dwordx4 v[120:123], v[30:31], off offset:3072
	s_waitcnt vmcnt(21)
; DI unsigned pk2(float lo, float hi) { f32x2 v = {lo, hi}; bf16x2_t r = __builtin_convertvector(v, bf16x2_t); return __builtin_bit_cast(unsigned, r); }
; DI f32x4 mfma(bf16x8 a, bf16x8 b, f32x4 c) { return __builtin_amdgcn_mfma_f32_16x16x32_bf16(a, b, c, 0, 0, 0); }
; DI void phase_compress(const Params& p, int l, char* smem) {
;     ...
; #pragma unroll 4
;         for (int ks = 0; ks < 64; ++ks) {
;             const int t = ks >> 1, db = (ks & 1) * 32 + fq * 8;
;             const u32x4 xv = *(const u32x4*)(xr + (size_t)t * DINP + db);
;             const f32x4 p0 = *(const f32x4*)(pos + t * 64 + db), p1 = *(const f32x4*)(pos + t * 64 + db + 4);
;             bf16x8 wf[4];
; #pragma unroll
;             for (int i = 0; i < 4; ++i) wf[i] = *(const bf16x8*)(w1 + (size_t)i * 16 * 2048 + ks * 32);
;             u32x4 xb;
;             xb[0] = pk2(__uint_as_float(xv[0] << 16) + p0[0], __uint_as_float(xv[0] & 0xffff0000u) + p0[1]);
;             xb[1] = pk2(__uint_as_float(xv[1] << 16) + p0[2], __uint_as_float(xv[1] & 0xffff0000u) + p0[3]);
;             xb[2] = pk2(__uint_as_float(xv[2] << 16) + p1[0], __uint_as_float(xv[2] & 0xffff0000u) + p1[1]);
;             xb[3] = pk2(__uint_as_float(xv[3] << 16) + p1[2], __uint_as_float(xv[3] & 0xffff0000u) + p1[3]);
;             const bf16x8 bx = __builtin_bit_cast(bf16x8, xb);
; #pragma unroll
;             for (int i = 0; i < 4; ++i) acc[i] = mfma(wf[i], bx, acc[i]);
;         }
	v_lshlrev_b32_e32 v4, 16, v124
	v_and_b32_e32 v5, 0xffff0000, v124
	v_pk_add_f32 v[4:5], v[128:129], v[4:5]
	s_nop 0
	v_cvt_pk_bf16_f32 v124, v4, v5
	v_lshlrev_b32_e32 v6, 16, v125
	v_and_b32_e32 v7, 0xffff0000, v125
	v_pk_add_f32 v[6:7], v[130:131], v[6:7]
	s_nop 0
	v_cvt_pk_bf16_f32 v125, v6, v7
	v_lshlrev_b32_e32 v4, 16, v126
	v_and_b32_e32 v5, 0xffff0000, v126
	v_pk_add_f32 v[4:5], v[132:133], v[4:5]
	s_nop 0
	v_cvt_pk_bf16_f32 v126, v4, v5
	v_lshlrev_b32_e32 v6, 16, v127
	v_and_b32_e32 v7, 0xffff0000, v127
	v_pk_add_f32 v[6:7], v[134:135], v[6:7]
	s_nop 0
	v_cvt_pk_bf16_f32 v127, v6, v7
	s_nop 1
	v_mfma_f32_16x16x32_bf16 v[16:19], v[136:139], v[124:127], v[16:19]
	v_mfma_f32_16x16x32_bf16 v[0:3], v[140:143], v[124:127], v[0:3]
	v_mfma_f32_16x16x32_bf16 v[12:15], v[144:147], v[124:127], v[12:15]
	v_mfma_f32_16x16x32_bf16 v[8:11], v[148:151], v[124:127], v[8:11]
	global_load_dwordx4 v[124:127], v[22:23], off offset:1920
	global_load_dwordx4 v[132:135], v[36:37], off offset:272
	global_load_dwordx4 v[128:131], v[36:37], off offset:256
	global_load_dwordx4 v[136:139], v[32:33], off
	global_load_dwordx4 v[140:143], v[32:33], off offset:1024
	global_load_dwordx4 v[144:147], v[32:33], off offset:2048
	global_load_dwordx4 v[148:151], v[32:33], off offset:3072
	s_waitcnt vmcnt(21)
	v_lshlrev_b32_e32 v4, 16, v152
	v_and_b32_e32 v5, 0xffff0000, v152
	v_pk_add_f32 v[4:5], v[156:157], v[4:5]
	s_nop 0
	v_cvt_pk_bf16_f32 v152, v4, v5
	v_lshlrev_b32_e32 v6, 16, v153
	v_and_b32_e32 v7, 0xffff0000, v153
	v_pk_add_f32 v[6:7], v[158:159], v[6:7]
	s_nop 0
	v_cvt_pk_bf16_f32 v153, v6, v7
	v_lshlrev_b32_e32 v4, 16, v154
	v_and_b32_e32 v5, 0xffff0000, v154
	v_pk_add_f32 v[4:5], v[160:161], v[4:5]
	s_nop 0
	v_cvt_pk_bf16_f32 v154, v4, v5
	v_lshlrev_b32_e32 v6, 16, v155
	v_and_b32_e32 v7, 0xffff0000, v155
	v_pk_add_f32 v[6:7], v[162:163], v[6:7]
	s_nop 0
	v_cvt_pk_bf16_f32 v155, v6, v7
	s_nop 1
	v_mfma_f32_16x16x32_bf16 v[16:19], v[164:167], v[152:155], v[16:19]
	v_mfma_f32_16x16x32_bf16 v[0:3], v[168:171], v[152:155], v[0:3]
	v_mfma_f32_16x16x32_bf16 v[12:15], v[172:175], v[152:155], v[12:15]
	v_mfma_f32_16x16x32_bf16 v[8:11], v[176:179], v[152:155], v[8:11]
	global_load_dwordx4 v[152:155], v[22:23], off offset:1984
	global_load_dwordx4 v[160:163], v[36:37], off offset:400
	global_load_dwordx4 v[156:159], v[36:37], off offset:384
	global_load_dwordx4 v[164:167], v[34:35], off
	global_load_dwordx4 v[168:171], v[34:35], off offset:1024
	global_load_dwordx4 v[172:175], v[34:35], off offset:2048
	global_load_dwordx4 v[176:179], v[34:35], off offset:3072
	s_mov_b64 s[24:25], 0x3000
	v_lshl_add_u64 v[20:21], v[20:21], 0, s[24:25]
	v_lshl_add_u64 v[22:23], v[22:23], 0, s[24:25]
	s_mov_b64 s[24:25], 0x10000
	v_lshl_add_u64 v[28:29], v[28:29], 0, s[24:25]
	v_lshl_add_u64 v[30:31], v[30:31], 0, s[24:25]
	v_lshl_add_u64 v[32:33], v[32:33], 0, s[24:25]
	v_lshl_add_u64 v[34:35], v[34:35], 0, s[24:25]
	s_mov_b64 s[24:25], 0x200
	v_lshl_add_u64 v[36:37], v[36:37], 0, s[24:25]
	s_add_i32 s14, s14, 1
	s_cmp_lt_u32 s14, 15
	s_cbranch_scc1 .Lcmp_loop
	s_waitcnt vmcnt(21)
	v_lshlrev_b32_e32 v4, 16, v24
	v_and_b32_e32 v5, 0xffff0000, v24
	v_pk_add_f32 v[4:5], v[76:77], v[4:5]
	s_nop 0
	v_cvt_pk_bf16_f32 v24, v4, v5
	v_lshlrev_b32_e32 v6, 16, v25
	v_and_b32_e32 v7, 0xffff0000, v25
	v_pk_add_f32 v[6:7], v[78:79], v[6:7]
	s_nop 0
	v_cvt_pk_bf16_f32 v25, v6, v7
	v_lshlrev_b32_e32 v4, 16, v26
	v_and_b32_e32 v5, 0xffff0000, v26
	v_pk_add_f32 v[4:5], v[38:39], v[4:5]
	s_nop 0
	v_cvt_pk_bf16_f32 v26, v4, v5
	v_lshlrev_b32_e32 v6, 16, v27
	v_and_b32_e32 v7, 0xffff0000, v27
	v_pk_add_f32 v[6:7], v[40:41], v[6:7]
	s_nop 0
	v_cvt_pk_bf16_f32 v27, v6, v7
	s_nop 1
	v_mfma_f32_16x16x32_bf16 v[16:19], v[80:83], v[24:27], v[16:19]
	v_mfma_f32_16x16x32_bf16 v[0:3], v[84:87], v[24:27], v[0:3]
	v_mfma_f32_16x16x32_bf16 v[12:15], v[88:91], v[24:27], v[12:15]
	v_mfma_f32_16x16x32_bf16 v[8:11], v[92:95], v[24:27], v[8:11]
	s_waitcnt vmcnt(14)
	v_lshlrev_b32_e32 v4, 16, v96
	v_and_b32_e32 v5, 0xffff0000, v96
	v_pk_add_f32 v[4:5], v[100:101], v[4:5]
	s_nop 0
	v_cvt_pk_bf16_f32 v96, v4, v5
	v_lshlrev_b32_e32 v6, 16, v97
	v_and_b32_e32 v7, 0xffff0000, v97
	v_pk_add_f32 v[6:7], v[102:103], v[6:7]
	s_nop 0
	v_cvt_pk_bf16_f32 v97, v6, v7
	v_lshlrev_b32_e32 v4, 16, v98
	v_and_b32_e32 v5, 0xffff0000, v98
	v_pk_add_f32 v[4:5], v[104:105], v[4:5]
	s_nop 0
	v_cvt_pk_bf16_f32 v98, v4, v5
	v_lshlrev_b32_e32 v6, 16, v99
	v_and_b32_e32 v7, 0xffff0000, v99
	v_pk_add_f32 v[6:7], v[106:107], v[6:7]
	s_nop 0
	v_cvt_pk_bf16_f32 v99, v6, v7
	s_nop 1
	v_mfma_f32_16x16x32_bf16 v[16:19], v[108:111], v[96:99], v[16:19]
	v_mfma_f32_16x16x32_bf16 v[0:3], v[112:115], v[96:99], v[0:3]
	v_mfma_f32_16x16x32_bf16 v[12:15], v[116:119], v[96:99], v[12:15]
	v_mfma_f32_16x16x32_bf16 v[8:11], v[120:123], v[96:99], v[8:11]
	s_waitcnt vmcnt(7)
	v_lshlrev_b32_e32 v4, 16, v124
	v_and_b32_e32 v5, 0xffff0000, v124
	v_pk_add_f32 v[4:5], v[128:129], v[4:5]
	s_nop 0
	v_cvt_pk_bf16_f32 v124, v4, v5
	v_lshlrev_b32_e32 v6, 16, v125
	v_and_b32_e32 v7, 0xffff0000, v125
	v_pk_add_f32 v[6:7], v[130:131], v[6:7]
	s_nop 0
	v_cvt_pk_bf16_f32 v125, v6, v7
	v_lshlrev_b32_e32 v4, 16, v126
	v_and_b32_e32 v5, 0xffff0000, v126
	v_pk_add_f32 v[4:5], v[132:133], v[4:5]
	s_nop 0
	v_cvt_pk_bf16_f32 v126, v4, v5
	v_lshlrev_b32_e32 v6, 16, v127
	v_and_b32_e32 v7, 0xffff0000, v127
	v_pk_add_f32 v[6:7], v[134:135], v[6:7]
	s_nop 0
	v_cvt_pk_bf16_f32 v127, v6, v7
	s_nop 1
	v_mfma_f32_16x16x32_bf16 v[16:19], v[136:139], v[124:127], v[16:19]
	v_mfma_f32_16x16x32_bf16 v[0:3], v[140:143], v[124:127], v[0:3]
	v_mfma_f32_16x16x32_bf16 v[12:15], v[144:147], v[124:127], v[12:15]
	v_mfma_f32_16x16x32_bf16 v[8:11], v[148:151], v[124:127], v[8:11]
	s_waitcnt vmcnt(0)
; DI f32x4 mfma(bf16x8 a, bf16x8 b, f32x4 c) { return __builtin_amdgcn_mfma_f32_16x16x32_bf16(a, b, c, 0, 0, 0); }
; DI float siluf_(float x) { return x / (1.f + __expf(-x)); }
; DI void phase_compress(const Params& p, int l, char* smem) {
;     ...
;             for (int i = 0; i < 4; ++i) acc[i] = mfma(wf[i], bx, acc[i]);
;         }
;         f32x4 o[4];
; #pragma unroll
;         for (int i = 0; i < 4; ++i) o[i] = (f32x4){0.f, 0.f, 0.f, 0.f};
; #pragma unroll
;         for (int kk = 0; kk < 2; ++kk) {
;             const int k2 = wave * 2 + kk;
;             f32x4 a = acc[2 * kk], c2 = acc[2 * kk + 1];
; #pragma unroll
;             for (int e = 0; e < 4; ++e) { a[e] = siluf_(a[e]); c2[e] = siluf_(c2[e]); }
;             const bf16x8 hb = pack2(a, c2);
; #pragma unroll
;             for (int t2 = 0; t2 < 4; ++t2) {
;                 const bf16_t* wr = w2 + (size_t)(t2 * 16 + fr) * 256 + k2 * 32 + fq * 4;
;                 const u32x2 lo = *(const u32x2*)wr, hi = *(const u32x2*)(wr + 16);
;                 u32x4 wv; wv[0] = lo[0]; wv[1] = lo[1]; wv[2] = hi[0]; wv[3] = hi[1];
;                 o[t2] = mfma(__builtin_bit_cast(bf16x8, wv), hb, o[t2]);
;             }
;         }
	v_lshlrev_b32_e32 v4, 16, v152
	v_and_b32_e32 v5, 0xffff0000, v152
	v_pk_add_f32 v[4:5], v[156:157], v[4:5]
	s_nop 0
	v_cvt_pk_bf16_f32 v152, v4, v5
	v_lshlrev_b32_e32 v6, 16, v153
	v_and_b32_e32 v7, 0xffff0000, v153
	v_pk_add_f32 v[6:7], v[158:159], v[6:7]
	s_nop 0
	v_cvt_pk_bf16_f32 v153, v6, v7
	v_lshlrev_b32_e32 v4, 16, v154
	v_and_b32_e32 v5, 0xffff0000, v154
	v_pk_add_f32 v[4:5], v[160:161], v[4:5]
	s_nop 0
	v_cvt_pk_bf16_f32 v154, v4, v5
	v_lshlrev_b32_e32 v6, 16, v155
	v_and_b32_e32 v7, 0xffff0000, v155
	v_pk_add_f32 v[6:7], v[162:163], v[6:7]
	s_nop 0
	v_cvt_pk_bf16_f32 v155, v6, v7
	s_nop 1
	v_mfma_f32_16x16x32_bf16 v[16:19], v[164:167], v[152:155], v[16:19]
	v_mfma_f32_16x16x32_bf16 v[0:3], v[168:171], v[152:155], v[0:3]
	v_mfma_f32_16x16x32_bf16 v[12:15], v[172:175], v[152:155], v[12:15]
	v_mfma_f32_16x16x32_bf16 v[8:11], v[176:179], v[152:155], v[8:11]
	s_nop 7
	s_nop 2
	v_mul_f32_e32 v5, 0xbfb8aa3b, v0
	v_mul_f32_e32 v4, 0xbfb8aa3b, v16
	v_exp_f32_e32 v6, v5
	v_mul_f32_e32 v5, 0xbfb8aa3b, v17
	v_exp_f32_e32 v4, v4
	v_exp_f32_e32 v5, v5
	s_lshl_b64 s[10:11], s[10:11], 15
	v_lshl_add_u64 v[24:25], v[44:45], 0, s[10:11]
	v_mov_b32_e32 v57, v189
	v_pk_add_f32 v[4:5], v[4:5], 1.0 op_sel_hi:[1,0]
	v_lshl_add_u64 v[26:27], v[24:25], 0, v[56:57]
	v_div_scale_f32 v7, s[14:15], v5, v5, v17
	v_rcp_f32_e32 v20, v7
	v_mov_b32_e32 v59, v189
	v_mov_b32_e32 v61, v189
	v_mov_b32_e32 v63, v189
	v_fma_f32 v21, -v7, v20, 1.0
	v_fmac_f32_e32 v20, v21, v20
	v_div_scale_f32 v21, vcc, v17, v5, v17
	v_mul_f32_e32 v22, v21, v20
	v_fma_f32 v23, -v7, v22, v21
	v_fmac_f32_e32 v22, v23, v20
	v_fma_f32 v7, -v7, v22, v21
	v_div_fmas_f32 v7, v7, v20, v22
	v_div_fixup_f32 v17, v7, v5, v17
	v_div_scale_f32 v5, s[14:15], v4, v4, v16
	v_rcp_f32_e32 v7, v5
	v_lshl_add_u64 v[30:31], v[24:25], 0, v[62:63]
	v_fma_f32 v20, -v5, v7, 1.0
	v_fmac_f32_e32 v7, v20, v7
	v_div_scale_f32 v20, vcc, v16, v4, v16
	v_mul_f32_e32 v21, v20, v7
	v_fma_f32 v22, -v5, v21, v20
	v_fmac_f32_e32 v21, v22, v7
	v_fma_f32 v5, -v5, v21, v20
	v_div_fmas_f32 v5, v5, v7, v21
	v_div_fixup_f32 v16, v5, v4, v16
	v_mul_f32_e32 v4, 0xbfb8aa3b, v1
	v_exp_f32_e32 v7, v4
	s_nop 0
	v_pk_add_f32 v[4:5], v[6:7], 1.0 op_sel_hi:[1,0]
	s_nop 0
	v_div_scale_f32 v6, s[14:15], v5, v5, v1
	v_rcp_f32_e32 v7, v6
	s_nop 0
	v_fma_f32 v20, -v6, v7, 1.0
	v_fmac_f32_e32 v7, v20, v7
	v_div_scale_f32 v20, vcc, v1, v5, v1
	v_mul_f32_e32 v21, v20, v7
	v_fma_f32 v22, -v6, v21, v20
	v_fmac_f32_e32 v21, v22, v7
	v_fma_f32 v6, -v6, v21, v20
	v_div_fmas_f32 v6, v6, v7, v21
	v_div_fixup_f32 v6, v6, v5, v1
	v_div_scale_f32 v1, s[14:15], v4, v4, v0
	v_rcp_f32_e32 v5, v1
	s_nop 0
	v_fma_f32 v7, -v1, v5, 1.0
	v_fmac_f32_e32 v5, v7, v5
	v_div_scale_f32 v7, vcc, v0, v4, v0
	v_mul_f32_e32 v20, v7, v5
	v_fma_f32 v21, -v1, v20, v7
	v_fmac_f32_e32 v20, v21, v5
	v_fma_f32 v1, -v1, v20, v7
	v_div_fmas_f32 v1, v1, v5, v20
	v_div_fixup_f32 v7, v1, v4, v0
	v_mul_f32_e32 v1, 0xbfb8aa3b, v2
	v_mul_f32_e32 v0, 0xbfb8aa3b, v18
	v_exp_f32_e32 v4, v1
	v_mul_f32_e32 v1, 0xbfb8aa3b, v19
	v_exp_f32_e32 v0, v0
	v_exp_f32_e32 v1, v1
	s_nop 0
	v_pk_add_f32 v[0:1], v[0:1], 1.0 op_sel_hi:[1,0]
	s_nop 0
	v_div_scale_f32 v5, s[14:15], v1, v1, v19
	v_rcp_f32_e32 v20, v5
	s_nop 0
	v_fma_f32 v21, -v5, v20, 1.0
	v_fmac_f32_e32 v20, v21, v20
	v_div_scale_f32 v21, vcc, v19, v1, v19
	v_mul_f32_e32 v22, v21, v20
	v_fma_f32 v23, -v5, v22, v21
	v_fmac_f32_e32 v22, v23, v20
	v_fma_f32 v5, -v5, v22, v21
	v_div_fmas_f32 v5, v5, v20, v22
	v_div_fixup_f32 v19, v5, v1, v19
	v_div_scale_f32 v1, s[14:15], v0, v0, v18
	v_rcp_f32_e32 v5, v1
	s_nop 0
	v_fma_f32 v20, -v1, v5, 1.0
	v_fmac_f32_e32 v5, v20, v5
	v_div_scale_f32 v20, vcc, v18, v0, v18
	v_mul_f32_e32 v21, v20, v5
	v_fma_f32 v22, -v1, v21, v20
	v_fmac_f32_e32 v21, v22, v5
	v_fma_f32 v1, -v1, v21, v20
	v_div_fmas_f32 v1, v1, v5, v21
	v_div_fixup_f32 v18, v1, v0, v18
	v_mul_f32_e32 v0, 0xbfb8aa3b, v3
	v_exp_f32_e32 v5, v0
	s_nop 0
	v_pk_add_f32 v[0:1], v[4:5], 1.0 op_sel_hi:[1,0]
	s_nop 0
	v_div_scale_f32 v4, s[14:15], v1, v1, v3
	v_rcp_f32_e32 v5, v4
	s_nop 0
	v_fma_f32 v20, -v4, v5, 1.0
	v_fmac_f32_e32 v5, v20, v5
	v_div_scale_f32 v20, vcc, v3, v1, v3
	v_mul_f32_e32 v21, v20, v5
	v_fma_f32 v22, -v4, v21, v20
	v_fmac_f32_e32 v21, v22, v5
	v_fma_f32 v4, -v4, v21, v20
	v_div_fmas_f32 v4, v4, v5, v21
	v_div_fixup_f32 v3, v4, v1, v3
	v_div_scale_f32 v1, s[14:15], v0, v0, v2
	v_rcp_f32_e32 v4, v1
	s_nop 0
	v_fma_f32 v5, -v1, v4, 1.0
	v_fmac_f32_e32 v4, v5, v4
	v_div_scale_f32 v5, vcc, v2, v0, v2
	v_mul_f32_e32 v20, v5, v4
	v_fma_f32 v21, -v1, v20, v5
	v_fmac_f32_e32 v20, v21, v4
	v_fma_f32 v1, -v1, v20, v5
	v_div_fmas_f32 v1, v1, v4, v20
	v_div_fixup_f32 v4, v1, v0, v2
	v_cvt_pk_bf16_f32 v2, v7, v6
	v_cvt_pk_bf16_f32 v3, v4, v3
	global_load_dwordx2 v[4:5], v[26:27], off
	global_load_dwordx2 v[6:7], v[26:27], off offset:32
	v_cvt_pk_bf16_f32 v0, v16, v17
	v_cvt_pk_bf16_f32 v1, v18, v19
	s_waitcnt vmcnt(0)
	s_nop 0
	v_mfma_f32_16x16x32_bf16 v[16:19], v[4:7], v[0:3], 0
	v_lshl_add_u64 v[6:7], v[24:25], 0, v[58:59]
	global_load_dwordx2 v[4:5], v[6:7], off
	s_nop 0
	global_load_dwordx2 v[6:7], v[6:7], off offset:32
	s_waitcnt vmcnt(0)
	v_mfma_f32_16x16x32_bf16 v[20:23], v[4:7], v[0:3], 0
	v_lshl_add_u64 v[6:7], v[24:25], 0, v[60:61]
	global_load_dwordx2 v[4:5], v[6:7], off
	s_nop 0
	global_load_dwordx2 v[6:7], v[6:7], off offset:32
	s_nop 0
	global_load_dwordx2 v[28:29], v[30:31], off
	s_nop 0
	global_load_dwordx2 v[30:31], v[30:31], off offset:32
	v_lshl_add_u64 v[24:25], v[24:25], 0, 64
	s_waitcnt vmcnt(2)
	v_mfma_f32_16x16x32_bf16 v[4:7], v[4:7], v[0:3], 0
	s_waitcnt vmcnt(0)
; DI f32x4 mfma(bf16x8 a, bf16x8 b, f32x4 c) { return __builtin_amdgcn_mfma_f32_16x16x32_bf16(a, b, c, 0, 0, 0); }
; DI float siluf_(float x) { return x / (1.f + __expf(-x)); }
; DI void phase_compress(const Params& p, int l, char* smem) {
;     ...
;         for (int kk = 0; kk < 2; ++kk) {
;             const int k2 = wave * 2 + kk;
;             f32x4 a = acc[2 * kk], c2 = acc[2 * kk + 1];
; #pragma unroll
;             for (int e = 0; e < 4; ++e) { a[e] = siluf_(a[e]); c2[e] = siluf_(c2[e]); }
;             const bf16x8 hb = pack2(a, c2);
; #pragma unroll
;             for (int t2 = 0; t2 < 4; ++t2) {
;                 const bf16_t* wr = w2 + (size_t)(t2 * 16 + fr) * 256 + k2 * 32 + fq * 4;
;                 const u32x2 lo = *(const u32x2*)wr, hi = *(const u32x2*)(wr + 16);
;                 u32x4 wv; wv[0] = lo[0]; wv[1] = lo[1]; wv[2] = hi[0]; wv[3] = hi[1];
;                 o[t2] = mfma(__builtin_bit_cast(bf16x8, wv), hb, o[t2]);
;             }
;         }
; #pragma unroll
;         for (int t2 = 0; t2 < 4; ++t2)
; #pragma unroll
;             for (int e = 0; e < 4; ++e) red[(wave * 16 + t2 * 4 + e) * 64 + lane] = o[t2][e];
;         __syncthreads();
	v_mfma_f32_16x16x32_bf16 v[0:3], v[28:31], v[0:3], 0
	v_mul_f32_e32 v29, 0xbfb8aa3b, v8
	v_mul_f32_e32 v28, 0xbfb8aa3b, v12
	v_exp_f32_e32 v30, v29
	v_mul_f32_e32 v29, 0xbfb8aa3b, v13
	v_exp_f32_e32 v28, v28
	v_exp_f32_e32 v29, v29
	s_nop 0
	v_pk_add_f32 v[28:29], v[28:29], 1.0 op_sel_hi:[1,0]
	s_nop 0
	v_div_scale_f32 v31, s[10:11], v29, v29, v13
	v_rcp_f32_e32 v32, v31
	s_nop 0
	v_fma_f32 v33, -v31, v32, 1.0
	v_fmac_f32_e32 v32, v33, v32
	v_div_scale_f32 v33, vcc, v13, v29, v13
	v_mul_f32_e32 v34, v33, v32
	v_fma_f32 v35, -v31, v34, v33
	v_fmac_f32_e32 v34, v35, v32
	v_fma_f32 v31, -v31, v34, v33
	v_div_fmas_f32 v31, v31, v32, v34
	v_div_fixup_f32 v29, v31, v29, v13
	v_div_scale_f32 v13, s[10:11], v28, v28, v12
	v_rcp_f32_e32 v31, v13
	s_nop 0
	v_fma_f32 v32, -v13, v31, 1.0
	v_fmac_f32_e32 v31, v32, v31
	v_div_scale_f32 v32, vcc, v12, v28, v12
	v_mul_f32_e32 v33, v32, v31
	v_fma_f32 v34, -v13, v33, v32
	v_fmac_f32_e32 v33, v34, v31
	v_fma_f32 v13, -v13, v33, v32
	v_div_fmas_f32 v13, v13, v31, v33
	v_div_fixup_f32 v28, v13, v28, v12
	v_mul_f32_e32 v12, 0xbfb8aa3b, v9
	v_exp_f32_e32 v31, v12
	s_nop 0
	v_pk_add_f32 v[12:13], v[30:31], 1.0 op_sel_hi:[1,0]
	s_nop 0
	v_div_scale_f32 v30, s[10:11], v13, v13, v9
	v_rcp_f32_e32 v31, v30
	s_nop 0
	v_fma_f32 v32, -v30, v31, 1.0
	v_fmac_f32_e32 v31, v32, v31
	v_div_scale_f32 v32, vcc, v9, v13, v9
	v_mul_f32_e32 v33, v32, v31
	v_fma_f32 v34, -v30, v33, v32
	v_fmac_f32_e32 v33, v34, v31
	v_fma_f32 v30, -v30, v33, v32
	v_div_fmas_f32 v30, v30, v31, v33
	v_div_fixup_f32 v30, v30, v13, v9
	v_div_scale_f32 v9, s[10:11], v12, v12, v8
	v_rcp_f32_e32 v13, v9
	s_nop 0
	v_fma_f32 v31, -v9, v13, 1.0
	v_fmac_f32_e32 v13, v31, v13
	v_div_scale_f32 v31, vcc, v8, v12, v8
	v_mul_f32_e32 v32, v31, v13
	v_fma_f32 v33, -v9, v32, v31
	v_fmac_f32_e32 v32, v33, v13
	v_fma_f32 v9, -v9, v32, v31
	v_div_fmas_f32 v9, v9, v13, v32
	v_div_fixup_f32 v31, v9, v12, v8
	v_mul_f32_e32 v9, 0xbfb8aa3b, v10
	v_mul_f32_e32 v8, 0xbfb8aa3b, v14
	v_exp_f32_e32 v12, v9
	v_mul_f32_e32 v9, 0xbfb8aa3b, v15
	v_exp_f32_e32 v8, v8
	v_exp_f32_e32 v9, v9
	s_nop 0
	v_pk_add_f32 v[8:9], v[8:9], 1.0 op_sel_hi:[1,0]
	s_nop 0
	v_div_scale_f32 v13, s[10:11], v9, v9, v15
	v_rcp_f32_e32 v32, v13
	s_nop 0
	v_fma_f32 v33, -v13, v32, 1.0
	v_fmac_f32_e32 v32, v33, v32
	v_div_scale_f32 v33, vcc, v15, v9, v15
	v_mul_f32_e32 v34, v33, v32
	v_fma_f32 v35, -v13, v34, v33
	v_fmac_f32_e32 v34, v35, v32
	v_fma_f32 v13, -v13, v34, v33
	v_div_fmas_f32 v13, v13, v32, v34
	v_div_fixup_f32 v15, v13, v9, v15
	v_div_scale_f32 v9, s[10:11], v8, v8, v14
	v_rcp_f32_e32 v13, v9
	s_nop 0
	v_fma_f32 v32, -v9, v13, 1.0
	v_fmac_f32_e32 v13, v32, v13
	v_div_scale_f32 v32, vcc, v14, v8, v14
	v_mul_f32_e32 v33, v32, v13
	v_fma_f32 v34, -v9, v33, v32
	v_fmac_f32_e32 v33, v34, v13
	v_fma_f32 v9, -v9, v33, v32
	v_div_fmas_f32 v9, v9, v13, v33
	v_div_fixup_f32 v14, v9, v8, v14
	v_mul_f32_e32 v8, 0xbfb8aa3b, v11
	v_exp_f32_e32 v13, v8
	s_nop 0
	v_pk_add_f32 v[8:9], v[12:13], 1.0 op_sel_hi:[1,0]
	s_nop 0
	v_div_scale_f32 v12, s[10:11], v9, v9, v11
	v_rcp_f32_e32 v13, v12
	s_nop 0
	v_fma_f32 v32, -v12, v13, 1.0
	v_fmac_f32_e32 v13, v32, v13
	v_div_scale_f32 v32, vcc, v11, v9, v11
	v_mul_f32_e32 v33, v32, v13
	v_fma_f32 v34, -v12, v33, v32
	v_fmac_f32_e32 v33, v34, v13
	v_fma_f32 v12, -v12, v33, v32
	v_div_fmas_f32 v12, v12, v13, v33
	v_div_fixup_f32 v11, v12, v9, v11
	v_div_scale_f32 v9, s[10:11], v8, v8, v10
	v_rcp_f32_e32 v12, v9
	s_nop 0
	v_fma_f32 v13, -v9, v12, 1.0
	v_fmac_f32_e32 v12, v13, v12
	v_div_scale_f32 v13, vcc, v10, v8, v10
	v_mul_f32_e32 v32, v13, v12
	v_fma_f32 v33, -v9, v32, v13
	v_fmac_f32_e32 v32, v33, v12
	v_fma_f32 v9, -v9, v32, v13
	v_div_fmas_f32 v9, v9, v12, v32
	v_div_fixup_f32 v12, v9, v8, v10
	v_cvt_pk_bf16_f32 v9, v14, v15
	v_cvt_pk_bf16_f32 v11, v12, v11
	global_load_dwordx2 v[12:13], v[26:27], off offset:64
	global_load_dwordx2 v[14:15], v[26:27], off offset:96
	v_cvt_pk_bf16_f32 v8, v28, v29
	v_cvt_pk_bf16_f32 v10, v31, v30
	s_and_b64 vcc, exec, s[8:9]
	s_waitcnt vmcnt(0)
	v_mfma_f32_16x16x32_bf16 v[12:15], v[12:15], v[8:11], v[16:19]
	s_nop 2
	v_lshl_add_u64 v[18:19], v[24:25], 0, v[58:59]
	global_load_dwordx2 v[16:17], v[18:19], off
	s_nop 0
	global_load_dwordx2 v[18:19], v[18:19], off offset:32
	s_waitcnt vmcnt(0)
	v_mfma_f32_16x16x32_bf16 v[16:19], v[16:19], v[8:11], v[20:23]
	s_nop 2
	v_lshl_add_u64 v[22:23], v[24:25], 0, v[60:61]
	global_load_dwordx2 v[20:21], v[22:23], off
	s_nop 0
	global_load_dwordx2 v[22:23], v[22:23], off offset:32
	s_waitcnt vmcnt(0)
	v_mfma_f32_16x16x32_bf16 v[4:7], v[20:23], v[8:11], v[4:7]
	v_lshl_add_u64 v[22:23], v[24:25], 0, v[62:63]
	global_load_dwordx2 v[20:21], v[22:23], off
	s_nop 0
	global_load_dwordx2 v[22:23], v[22:23], off offset:32
	s_waitcnt vmcnt(0)
	v_mfma_f32_16x16x32_bf16 v[0:3], v[20:23], v[8:11], v[0:3]
	v_add_u32_e32 v8, s17, v73
	ds_write2st64_b32 v8, v12, v13 offset1:1
	ds_write2st64_b32 v8, v14, v15 offset0:2 offset1:3
	ds_write2st64_b32 v8, v16, v17 offset0:4 offset1:5
	ds_write2st64_b32 v8, v18, v19 offset0:6 offset1:7
	ds_write2st64_b32 v8, v4, v5 offset0:8 offset1:9
	ds_write2st64_b32 v8, v6, v7 offset0:10 offset1:11
	s_nop 0
	ds_write2st64_b32 v8, v0, v1 offset0:12 offset1:13
	ds_write2st64_b32 v8, v2, v3 offset0:14 offset1:15
	s_waitcnt lgkmcnt(0)
	s_barrier
	s_cbranch_vccz .LBB0_355
; DI bf16_t f2bf(float x) { unsigned u = __float_as_uint(x); u += 0x7fffu + ((u >> 16) & 1u); return (bf16_t)(u >> 16); }
; DI unsigned pk2(float lo, float hi) { f32x2 v = {lo, hi}; bf16x2_t r = __builtin_convertvector(v, bf16x2_t); return __builtin_bit_cast(unsigned, r); }
; DI int PINV(int s) { return (s & ~31) | ((s & 12) << 1) | ((s & 16) >> 2) | (s & 3); }
; DI void phase_compress(const Params& p, int l, char* smem) {
;     ...
;         if (wave == 0) {
; #pragma unroll
;             for (int t2 = 0; t2 < 4; ++t2)
; #pragma unroll
;                 for (int e = 0; e < 4; ++e) o[t2][e] += red[(16 + t2 * 4 + e) * 64 + lane] + red[(32 + t2 * 4 + e) * 64 + lane] + red[(48 + t2 * 4 + e) * 64 + lane];
;             if (kv == 0) {
;                 float ss = 0.f;
; #pragma unroll
;                 for (int t2 = 0; t2 < 4; ++t2)
; #pragma unroll
;                     for (int e = 0; e < 4; ++e) ss += o[t2][e] * o[t2][e];
;                 ss += __shfl_xor(ss, 16); ss += __shfl_xor(ss, 32);
;                 const float r = (c <= 1022) ? rsqrtf(ss * (1.f / 64.f) + 1e-6f) : 0.f;
;                 const float* g = p.k_norm + (l * 3 + 0) * 64;
; #pragma unroll
;                 for (int t2 = 0; t2 < 4; ++t2) {
;                     const int n2 = t2 * 16 + fq * 4;
;                     u32x2 o2; o2[0] = pk2(o[t2][0] * r * g[n2], o[t2][1] * r * g[n2 + 1]); o2[1] = pk2(o[t2][2] * r * g[n2 + 2], o[t2][3] * r * g[n2 + 3]);
;                     *(u32x2*)(p.kc + (((size_t)(b * 2 + kvh) * 1024) + c) * 64 + n2) = o2;
;                 }
;             } else {
;                 const float z = (c <= 1022) ? 1.f : 0.f;
;                 bf16_t* dst = p.vct + ((size_t)(b * 2 + kvh) * 16 + (c >> 6)) * 4096 + PINV(c & 63);
; #pragma unroll
;                 for (int t2 = 0; t2 < 4; ++t2)
; #pragma unroll
;                     for (int e = 0; e < 4; ++e) dst[(t2 * 16 + fq * 4 + e) * 64] = f2bf(o[t2][e] * z);
;             }
	ds_read2st64_b32 v[8:9], v73 offset0:16 offset1:17
	ds_read2st64_b32 v[10:11], v73 offset0:32 offset1:33
	ds_read2st64_b32 v[20:21], v73 offset0:48 offset1:49
	s_and_b32 s14, s22, 1
	s_mov_b64 s[10:11], -1
	s_cmpk_gt_u32 s13, 0xff
	s_waitcnt lgkmcnt(1)
	v_pk_add_f32 v[8:9], v[8:9], v[10:11]
	s_waitcnt lgkmcnt(0)
	v_pk_add_f32 v[8:9], v[8:9], v[20:21]
	s_nop 0
	v_pk_add_f32 v[12:13], v[12:13], v[8:9]
	ds_read2st64_b32 v[8:9], v73 offset0:18 offset1:19
	ds_read2st64_b32 v[10:11], v73 offset0:34 offset1:35
	ds_read2st64_b32 v[20:21], v73 offset0:50 offset1:51
	s_waitcnt lgkmcnt(1)
	v_pk_add_f32 v[8:9], v[8:9], v[10:11]
	s_waitcnt lgkmcnt(0)
	v_pk_add_f32 v[8:9], v[8:9], v[20:21]
	s_nop 0
	v_pk_add_f32 v[10:11], v[14:15], v[8:9]
	ds_read2st64_b32 v[8:9], v73 offset0:20 offset1:21
	ds_read2st64_b32 v[14:15], v73 offset0:36 offset1:37
	ds_read2st64_b32 v[20:21], v73 offset0:52 offset1:53
	s_waitcnt lgkmcnt(1)
	v_pk_add_f32 v[8:9], v[8:9], v[14:15]
	s_waitcnt lgkmcnt(0)
	v_pk_add_f32 v[8:9], v[8:9], v[20:21]
	s_nop 0
	v_pk_add_f32 v[8:9], v[16:17], v[8:9]
	ds_read2st64_b32 v[14:15], v73 offset0:22 offset1:23
	ds_read2st64_b32 v[16:17], v73 offset0:38 offset1:39
	ds_read2st64_b32 v[20:21], v73 offset0:54 offset1:55
	s_waitcnt lgkmcnt(1)
	v_pk_add_f32 v[14:15], v[14:15], v[16:17]
	s_waitcnt lgkmcnt(0)
	v_pk_add_f32 v[14:15], v[14:15], v[20:21]
	s_nop 0
	v_pk_add_f32 v[14:15], v[18:19], v[14:15]
	ds_read2st64_b32 v[16:17], v73 offset0:24 offset1:25
	ds_read2st64_b32 v[18:19], v73 offset0:40 offset1:41
	ds_read2st64_b32 v[20:21], v73 offset0:56 offset1:57
	s_waitcnt lgkmcnt(1)
	v_pk_add_f32 v[16:17], v[16:17], v[18:19]
	s_waitcnt lgkmcnt(0)
	v_pk_add_f32 v[16:17], v[16:17], v[20:21]
	s_nop 0
	v_pk_add_f32 v[4:5], v[4:5], v[16:17]
	ds_read2st64_b32 v[16:17], v73 offset0:26 offset1:27
	ds_read2st64_b32 v[18:19], v73 offset0:42 offset1:43
	ds_read2st64_b32 v[20:21], v73 offset0:58 offset1:59
	s_waitcnt lgkmcnt(1)
	v_pk_add_f32 v[16:17], v[16:17], v[18:19]
	s_waitcnt lgkmcnt(0)
	v_pk_add_f32 v[16:17], v[16:17], v[20:21]
	s_nop 0
	v_pk_add_f32 v[6:7], v[6:7], v[16:17]
	ds_read2st64_b32 v[16:17], v73 offset0:28 offset1:29
	ds_read2st64_b32 v[18:19], v73 offset0:44 offset1:45
	ds_read2st64_b32 v[20:21], v73 offset0:60 offset1:61
	s_waitcnt lgkmcnt(1)
	v_pk_add_f32 v[16:17], v[16:17], v[18:19]
	s_waitcnt lgkmcnt(0)
	v_pk_add_f32 v[16:17], v[16:17], v[20:21]
	s_nop 0
	v_pk_add_f32 v[0:1], v[0:1], v[16:17]
	ds_read2st64_b32 v[16:17], v73 offset0:30 offset1:31
	ds_read2st64_b32 v[18:19], v73 offset0:46 offset1:47
	ds_read2st64_b32 v[20:21], v73 offset0:62 offset1:63
	s_waitcnt lgkmcnt(1)
	v_pk_add_f32 v[16:17], v[16:17], v[18:19]
	s_waitcnt lgkmcnt(0)
	v_pk_add_f32 v[16:17], v[16:17], v[20:21]
	s_nop 0
	v_pk_add_f32 v[2:3], v[2:3], v[16:17]
	s_cbranch_scc0 .LBB0_361
	v_cndmask_b32_e64 v18, 1.0, 0, s[6:7]
	s_lshl_b32 s6, s20, 5
	s_lshl_b32 s7, s14, 4
	s_or_b32 s6, s6, s7
	s_lshr_b32 s7, s21, 6
	s_or_b32 s6, s6, s7
	v_readlane_b32 s52, v251, 0
	s_lshl_b32 s6, s6, 13
	v_readlane_b32 s62, v251, 10
	v_readlane_b32 s63, v251, 11
	s_add_u32 s6, s62, s6
	s_addc_u32 s7, s63, 0
	s_lshr_b32 s10, s19, 2
	s_and_b32 s10, s10, 4
	v_and_b32_e32 v16, 35, v75
	v_or3_b32 v16, s10, v74, v16
	v_lshlrev_b32_e32 v188, 1, v16
	v_mul_f32_e32 v19, v18, v12
	v_lshl_add_u64 v[16:17], s[6:7], 0, v[188:189]
	v_bfe_u32 v20, v19, 16, 1
	s_movk_i32 s6, 0x7fff
	v_mov_b32_e32 v65, v189
	v_add3_u32 v19, v19, v20, s6
	v_lshl_add_u64 v[16:17], v[16:17], 0, v[64:65]
	global_store_short_d16_hi v[16:17], v19, off
	v_mul_f32_e32 v19, v18, v13
	v_bfe_u32 v20, v19, 16, 1
	v_add3_u32 v19, v19, v20, s6
	global_store_short_d16_hi v[16:17], v19, off offset:128
	v_mul_f32_e32 v19, v18, v10
	v_bfe_u32 v20, v19, 16, 1
	v_add3_u32 v19, v19, v20, s6
	global_store_short_d16_hi v[16:17], v19, off offset:256
	v_mul_f32_e32 v19, v18, v11
	v_bfe_u32 v20, v19, 16, 1
	v_add3_u32 v19, v19, v20, s6
	global_store_short_d16_hi v[16:17], v19, off offset:384
	v_mul_f32_e32 v19, v18, v8
	v_bfe_u32 v20, v19, 16, 1
	v_add3_u32 v19, v19, v20, s6
	global_store_short_d16_hi v[16:17], v19, off offset:2048
	v_mul_f32_e32 v19, v18, v9
	v_bfe_u32 v20, v19, 16, 1
	v_add3_u32 v19, v19, v20, s6
	global_store_short_d16_hi v[16:17], v19, off offset:2176
	v_mul_f32_e32 v19, v18, v14
	v_bfe_u32 v20, v19, 16, 1
	v_add3_u32 v19, v19, v20, s6
	global_store_short_d16_hi v[16:17], v19, off offset:2304
	v_mul_f32_e32 v19, v18, v15
	v_bfe_u32 v20, v19, 16, 1
	v_add3_u32 v19, v19, v20, s6
	global_store_short_d16_hi v[16:17], v19, off offset:2432
	v_mul_f32_e32 v19, v18, v4
	v_bfe_u32 v20, v19, 16, 1
	v_add_co_u32_e32 v16, vcc, s35, v16
	v_add3_u32 v19, v19, v20, s6
	s_nop 0
	v_addc_co_u32_e32 v17, vcc, 0, v17, vcc
	global_store_short_d16_hi v[16:17], v19, off
	v_mul_f32_e32 v19, v18, v5
	v_bfe_u32 v20, v19, 16, 1
	v_add3_u32 v19, v19, v20, s6
	global_store_short_d16_hi v[16:17], v19, off offset:128
	v_mul_f32_e32 v19, v18, v6
	v_bfe_u32 v20, v19, 16, 1
	v_add3_u32 v19, v19, v20, s6
	global_store_short_d16_hi v[16:17], v19, off offset:256
	v_mul_f32_e32 v19, v18, v7
	v_bfe_u32 v20, v19, 16, 1
	v_add3_u32 v19, v19, v20, s6
	global_store_short_d16_hi v[16:17], v19, off offset:384
	v_mul_f32_e32 v19, v18, v0
	v_bfe_u32 v20, v19, 16, 1
	v_add3_u32 v19, v19, v20, s6
	global_store_short_d16_hi v[16:17], v19, off offset:2048
	v_mul_f32_e32 v19, v18, v1
	v_bfe_u32 v20, v19, 16, 1
	v_add3_u32 v19, v19, v20, s6
	global_store_short_d16_hi v[16:17], v19, off offset:2176
	v_mul_f32_e32 v19, v18, v2
	v_bfe_u32 v20, v19, 16, 1
	v_add3_u32 v19, v19, v20, s6
	v_mul_f32_e32 v18, v18, v3
	global_store_short_d16_hi v[16:17], v19, off offset:2304
	v_bfe_u32 v19, v18, 16, 1
	v_add3_u32 v18, v18, v19, s6
	v_readlane_b32 s53, v251, 1
	v_readlane_b32 s54, v251, 2
	v_readlane_b32 s55, v251, 3
	v_readlane_b32 s56, v251, 4
	v_readlane_b32 s57, v251, 5
	v_readlane_b32 s58, v251, 6
	v_readlane_b32 s59, v251, 7
	v_readlane_b32 s60, v251, 8
	v_readlane_b32 s61, v251, 9
	v_readlane_b32 s64, v251, 12
	v_readlane_b32 s65, v251, 13
	v_readlane_b32 s66, v251, 14
	v_readlane_b32 s67, v251, 15
	global_store_short_d16_hi v[16:17], v18, off offset:2432
	s_mov_b64 s[10:11], 0

; DI f32x4 mfma(bf16x8 a, bf16x8 b, f32x4 c) { return __builtin_amdgcn_mfma_f32_16x16x32_bf16(a, b, c, 0, 0, 0); }
; #define G_LOAD(PA, PB, STEP) do { _Pragma("unroll") for (int i_ = 0; i_ < 2; ++i_) ra[i_] = *(const u32x4*)((PA) + (size_t)(64 * i_) * K + (STEP) * 32); \
;         _Pragma("unroll") for (int i_ = 0; i_ < 4; ++i_) rb[i_] = *(const u32x4*)((PB) + (size_t)(64 * i_) * K + (STEP) * 32); } while (0)
; #define G_STORE(BUF) do { _Pragma("unroll") for (int i_ = 0; i_ < 2; ++i_) *(u32x4*)(sA + (BUF) * 128 * 40 + (lrow + 64 * i_) * 40 + lcc * 8) = ra[i_]; \
;         _Pragma("unroll") for (int i_ = 0; i_ < 4; ++i_) *(u32x4*)(sB + (BUF) * 256 * 40 + (lrow + 64 * i_) * 40 + lcc * 8) = rb[i_]; } while (0)
; template <int EPI> ...
;     ...
;         for (int kt = 0; kt < nk; ++kt) {
;             const int buf = kt & 1;
;             const bf16_t* a_ = sA + buf * 128 * 40 + (wr * 64 + fr) * 40 + fq * 8;
;             const bf16_t* b_ = sB + buf * 256 * 40 + (wc * 128 + fr) * 40 + fq * 8;
;             bf16x8 af[4];
; #pragma unroll
;             for (int i = 0; i < 4; ++i) af[i] = *(const bf16x8*)(a_ + i * 16 * 40);
; #pragma unroll
;             for (int jh = 0; jh < 2; ++jh) {
;                 bf16x8 bfr[4];
; #pragma unroll
;                 for (int j = 0; j < 4; ++j) bfr[j] = *(const bf16x8*)(b_ + (jh * 4 + j) * 16 * 40);
; #pragma unroll
;                 for (int i = 0; i < 4; ++i)
; #pragma unroll
;                     for (int j = 0; j < 4; ++j) acc[i][jh * 4 + j] = mfma(bfr[j], af[i], acc[i][jh * 4 + j]);
;             }
;             G_STORE(buf ^ 1);
;             {
;                 const bool cur = kt + 2 < nk;
;                 const bf16_t* pa = cur ? Ag : An; const bf16_t* pb = cur ? Bg : Bn;
;                 const int st = cur ? kt + 2 : kt + 2 - nk;
;                 G_LOAD(pa, pb, st);
;             }
;             __syncthreads();
;         }
.Lg691_top:
	s_setprio 0
	s_waitcnt lgkmcnt(4)
	v_mfma_f32_16x16x32_bf16 v[148:151], v[174:177], v[10:13], v[148:151]
	v_mfma_f32_16x16x32_bf16 v[116:119], v[174:177], v[14:17], v[116:119]
	v_mfma_f32_16x16x32_bf16 v[84:87], v[174:177], v[18:21], v[84:87]
	v_mfma_f32_16x16x32_bf16 v[52:55], v[174:177], v[154:157], v[52:55]
	v_mfma_f32_16x16x32_bf16 v[144:147], v[192:195], v[10:13], v[144:147]
	v_mfma_f32_16x16x32_bf16 v[112:115], v[192:195], v[14:17], v[112:115]
	v_mfma_f32_16x16x32_bf16 v[80:83], v[192:195], v[18:21], v[80:83]
	v_mfma_f32_16x16x32_bf16 v[48:51], v[192:195], v[154:157], v[48:51]
	v_mfma_f32_16x16x32_bf16 v[140:143], v[196:199], v[10:13], v[140:143]
	v_mfma_f32_16x16x32_bf16 v[108:111], v[196:199], v[14:17], v[108:111]
	v_mfma_f32_16x16x32_bf16 v[76:79], v[196:199], v[18:21], v[76:79]
	v_mfma_f32_16x16x32_bf16 v[44:47], v[196:199], v[154:157], v[44:47]
	v_mfma_f32_16x16x32_bf16 v[136:139], v[200:203], v[10:13], v[136:139]
	v_mfma_f32_16x16x32_bf16 v[104:107], v[200:203], v[14:17], v[104:107]
	v_mfma_f32_16x16x32_bf16 v[72:75], v[200:203], v[18:21], v[72:75]
	v_mfma_f32_16x16x32_bf16 v[40:43], v[200:203], v[154:157], v[40:43]
	s_waitcnt vmcnt(6)
	s_waitcnt lgkmcnt(0)
	s_barrier
	s_add_u32 s23, s21, 0x6000
	s_cmp_eq_u32 s23, 0x12000
	s_cselect_b32 s23, 0, s23
	v_add_u32_e32 v8, s23, v6
	v_add_u32_e32 v9, s23, v7
	ds_read_b128 v[174:177], v9
	ds_read_b128 v[192:195], v9 offset:1024
	ds_read_b128 v[196:199], v9 offset:2048
	ds_read_b128 v[200:203], v9 offset:3072
	s_cmp_eq_u32 s20, 29
	s_cbranch_scc1 .Lg691_sw
.Lg691_swret:
	s_add_u32 m0, s21, s22
	s_setprio 1
	v_mfma_f32_16x16x32_bf16 v[132:135], v[204:207], v[10:13], v[132:135]
	v_mfma_f32_16x16x32_bf16 v[128:131], v[232:235], v[10:13], v[128:131]
	v_mfma_f32_16x16x32_bf16 v[124:127], v[236:239], v[10:13], v[124:127]
	v_mfma_f32_16x16x32_bf16 v[120:123], v[240:243], v[10:13], v[120:123]
	ds_read_b128 v[10:13], v8
	v_mfma_f32_16x16x32_bf16 v[100:103], v[204:207], v[14:17], v[100:103]
	v_mfma_f32_16x16x32_bf16 v[96:99], v[232:235], v[14:17], v[96:99]
	v_mfma_f32_16x16x32_bf16 v[92:95], v[236:239], v[14:17], v[92:95]
	v_mfma_f32_16x16x32_bf16 v[88:91], v[240:243], v[14:17], v[88:91]
	ds_read_b128 v[14:17], v8 offset:1024
	v_mfma_f32_16x16x32_bf16 v[68:71], v[204:207], v[18:21], v[68:71]
	global_load_lds_dwordx4 v0, s[98:99]
	v_mfma_f32_16x16x32_bf16 v[64:67], v[232:235], v[18:21], v[64:67]
	global_load_lds_dwordx4 v1, s[98:99] offset:1024
	v_mfma_f32_16x16x32_bf16 v[60:63], v[236:239], v[18:21], v[60:63]
	global_load_lds_dwordx4 v2, s[100:101] offset:2048
	v_mfma_f32_16x16x32_bf16 v[56:59], v[240:243], v[18:21], v[56:59]
	global_load_lds_dwordx4 v3, s[100:101] offset:3072
	ds_read_b128 v[18:21], v8 offset:6144
	v_mfma_f32_16x16x32_bf16 v[36:39], v[204:207], v[154:157], v[36:39]
	s_add_u32 m0, m0, 0x1000
	v_mfma_f32_16x16x32_bf16 v[32:35], v[232:235], v[154:157], v[32:35]
	global_load_lds_dwordx4 v4, s[100:101]
	v_mfma_f32_16x16x32_bf16 v[28:31], v[236:239], v[154:157], v[28:31]
	global_load_lds_dwordx4 v5, s[100:101] offset:1024
	v_mfma_f32_16x16x32_bf16 v[24:27], v[240:243], v[154:157], v[24:27]
	ds_read_b128 v[154:157], v8 offset:7168
	ds_read_b128 v[204:207], v9 offset:6144
	ds_read_b128 v[232:235], v9 offset:7168
	ds_read_b128 v[236:239], v9 offset:8192
	ds_read_b128 v[240:243], v9 offset:9216
	s_add_u32 s98, s98, 0x40
	s_addc_u32 s99, s99, 0
	s_add_u32 s100, s100, 0x10000
	s_addc_u32 s101, s101, 0
	s_add_u32 s21, s21, 0x6000
	s_cmp_eq_u32 s21, 0x12000
	s_cselect_b32 s21, 0, s21
	s_add_u32 s20, s20, 1
	s_cmp_lt_u32 s20, 31
	s_cbranch_scc1 .Lg691_top
	s_setprio 0
	s_waitcnt lgkmcnt(4)
	v_mfma_f32_16x16x32_bf16 v[148:151], v[174:177], v[10:13], v[148:151]
	v_mfma_f32_16x16x32_bf16 v[116:119], v[174:177], v[14:17], v[116:119]
	v_mfma_f32_16x16x32_bf16 v[84:87], v[174:177], v[18:21], v[84:87]
	v_mfma_f32_16x16x32_bf16 v[52:55], v[174:177], v[154:157], v[52:55]
	v_mfma_f32_16x16x32_bf16 v[144:147], v[192:195], v[10:13], v[144:147]
	v_mfma_f32_16x16x32_bf16 v[112:115], v[192:195], v[14:17], v[112:115]
	v_mfma_f32_16x16x32_bf16 v[80:83], v[192:195], v[18:21], v[80:83]
	v_mfma_f32_16x16x32_bf16 v[48:51], v[192:195], v[154:157], v[48:51]
	v_mfma_f32_16x16x32_bf16 v[140:143], v[196:199], v[10:13], v[140:143]
	v_mfma_f32_16x16x32_bf16 v[108:111], v[196:199], v[14:17], v[108:111]
	v_mfma_f32_16x16x32_bf16 v[76:79], v[196:199], v[18:21], v[76:79]
	v_mfma_f32_16x16x32_bf16 v[44:47], v[196:199], v[154:157], v[44:47]
	v_mfma_f32_16x16x32_bf16 v[136:139], v[200:203], v[10:13], v[136:139]
	v_mfma_f32_16x16x32_bf16 v[104:107], v[200:203], v[14:17], v[104:107]
	v_mfma_f32_16x16x32_bf16 v[72:75], v[200:203], v[18:21], v[72:75]
	v_mfma_f32_16x16x32_bf16 v[40:43], v[200:203], v[154:157], v[40:43]
	s_waitcnt vmcnt(6)
	s_waitcnt lgkmcnt(0)
	s_barrier
	s_add_u32 m0, s21, s22
	s_setprio 1
	v_mfma_f32_16x16x32_bf16 v[132:135], v[204:207], v[10:13], v[132:135]
	v_mfma_f32_16x16x32_bf16 v[128:131], v[232:235], v[10:13], v[128:131]
	v_mfma_f32_16x16x32_bf16 v[124:127], v[236:239], v[10:13], v[124:127]
	v_mfma_f32_16x16x32_bf16 v[120:123], v[240:243], v[10:13], v[120:123]
	v_mfma_f32_16x16x32_bf16 v[100:103], v[204:207], v[14:17], v[100:103]
	v_mfma_f32_16x16x32_bf16 v[96:99], v[232:235], v[14:17], v[96:99]
	v_mfma_f32_16x16x32_bf16 v[92:95], v[236:239], v[14:17], v[92:95]
	v_mfma_f32_16x16x32_bf16 v[88:91], v[240:243], v[14:17], v[88:91]
	v_mfma_f32_16x16x32_bf16 v[68:71], v[204:207], v[18:21], v[68:71]
	global_load_lds_dwordx4 v0, s[98:99]
	v_mfma_f32_16x16x32_bf16 v[64:67], v[232:235], v[18:21], v[64:67]
	global_load_lds_dwordx4 v1, s[98:99] offset:1024
	v_mfma_f32_16x16x32_bf16 v[60:63], v[236:239], v[18:21], v[60:63]
	global_load_lds_dwordx4 v2, s[100:101] offset:2048
	v_mfma_f32_16x16x32_bf16 v[56:59], v[240:243], v[18:21], v[56:59]
	global_load_lds_dwordx4 v3, s[100:101] offset:3072
	v_mfma_f32_16x16x32_bf16 v[36:39], v[204:207], v[154:157], v[36:39]
	s_add_u32 m0, m0, 0x1000
	v_mfma_f32_16x16x32_bf16 v[32:35], v[232:235], v[154:157], v[32:35]
	global_load_lds_dwordx4 v4, s[100:101]
	v_mfma_f32_16x16x32_bf16 v[28:31], v[236:239], v[154:157], v[28:31]
	global_load_lds_dwordx4 v5, s[100:101] offset:1024
	v_mfma_f32_16x16x32_bf16 v[24:27], v[240:243], v[154:157], v[24:27]
	s_add_u32 s98, s98, 0x40
	s_addc_u32 s99, s99, 0
	s_add_u32 s100, s100, 0x10000
	s_addc_u32 s101, s101, 0
	s_add_u32 s21, s21, 0x6000
	s_cmp_eq_u32 s21, 0x12000
	s_cselect_b32 s21, 0, s21
	s_add_u32 s20, s20, 1
	s_branch .Lg691_end

; DI f32x4 mfma(bf16x8 a, bf16x8 b, f32x4 c) { return __builtin_amdgcn_mfma_f32_16x16x32_bf16(a, b, c, 0, 0, 0); }
; #define G_LOAD(PA, PB, STEP) do { _Pragma("unroll") for (int i_ = 0; i_ < 2; ++i_) ra[i_] = *(const u32x4*)((PA) + (size_t)(64 * i_) * K + (STEP) * 32); \
;         _Pragma("unroll") for (int i_ = 0; i_ < 4; ++i_) rb[i_] = *(const u32x4*)((PB) + (size_t)(64 * i_) * K + (STEP) * 32); } while (0)
; #define G_STORE(BUF) do { _Pragma("unroll") for (int i_ = 0; i_ < 2; ++i_) *(u32x4*)(sA + (BUF) * 128 * 40 + (lrow + 64 * i_) * 40 + lcc * 8) = ra[i_]; \
;         _Pragma("unroll") for (int i_ = 0; i_ < 4; ++i_) *(u32x4*)(sB + (BUF) * 256 * 40 + (lrow + 64 * i_) * 40 + lcc * 8) = rb[i_]; } while (0)
; template <int EPI> ...
;     ...
;         for (int kt = 0; kt < nk; ++kt) {
;             const int buf = kt & 1;
;             const bf16_t* a_ = sA + buf * 128 * 40 + (wr * 64 + fr) * 40 + fq * 8;
;             const bf16_t* b_ = sB + buf * 256 * 40 + (wc * 128 + fr) * 40 + fq * 8;
;             bf16x8 af[4];
; #pragma unroll
;             for (int i = 0; i < 4; ++i) af[i] = *(const bf16x8*)(a_ + i * 16 * 40);
; #pragma unroll
;             for (int jh = 0; jh < 2; ++jh) {
;                 bf16x8 bfr[4];
; #pragma unroll
;                 for (int j = 0; j < 4; ++j) bfr[j] = *(const bf16x8*)(b_ + (jh * 4 + j) * 16 * 40);
; #pragma unroll
;                 for (int i = 0; i < 4; ++i)
; #pragma unroll
;                     for (int j = 0; j < 4; ++j) acc[i][jh * 4 + j] = mfma(bfr[j], af[i], acc[i][jh * 4 + j]);
;             }
;             G_STORE(buf ^ 1);
;             {
;                 const bool cur = kt + 2 < nk;
;                 const bf16_t* pa = cur ? Ag : An; const bf16_t* pb = cur ? Bg : Bn;
;                 const int st = cur ? kt + 2 : kt + 2 - nk;
;                 G_LOAD(pa, pb, st);
;             }
;             __syncthreads();
;         }
.Lg778_top:
	s_setprio 0
	s_waitcnt lgkmcnt(4)
	v_mfma_f32_16x16x32_bf16 v[148:151], v[172:175], v[10:13], v[148:151]
	v_mfma_f32_16x16x32_bf16 v[116:119], v[172:175], v[14:17], v[116:119]
	v_mfma_f32_16x16x32_bf16 v[84:87], v[172:175], v[18:21], v[84:87]
	v_mfma_f32_16x16x32_bf16 v[52:55], v[172:175], v[152:155], v[52:55]
	v_mfma_f32_16x16x32_bf16 v[144:147], v[176:179], v[10:13], v[144:147]
	v_mfma_f32_16x16x32_bf16 v[112:115], v[176:179], v[14:17], v[112:115]
	v_mfma_f32_16x16x32_bf16 v[80:83], v[176:179], v[18:21], v[80:83]
	v_mfma_f32_16x16x32_bf16 v[48:51], v[176:179], v[152:155], v[48:51]
	v_mfma_f32_16x16x32_bf16 v[140:143], v[180:183], v[10:13], v[140:143]
	v_mfma_f32_16x16x32_bf16 v[108:111], v[180:183], v[14:17], v[108:111]
	v_mfma_f32_16x16x32_bf16 v[76:79], v[180:183], v[18:21], v[76:79]
	v_mfma_f32_16x16x32_bf16 v[44:47], v[180:183], v[152:155], v[44:47]
	v_mfma_f32_16x16x32_bf16 v[136:139], v[184:187], v[10:13], v[136:139]
	v_mfma_f32_16x16x32_bf16 v[104:107], v[184:187], v[14:17], v[104:107]
	v_mfma_f32_16x16x32_bf16 v[72:75], v[184:187], v[18:21], v[72:75]
	v_mfma_f32_16x16x32_bf16 v[40:43], v[184:187], v[152:155], v[40:43]
	s_waitcnt vmcnt(6)
	s_waitcnt lgkmcnt(0)
	s_barrier
	s_add_u32 s18, s16, 0x6000
	s_cmp_eq_u32 s18, 0x12000
	s_cselect_b32 s18, 0, s18
	v_add_u32_e32 v8, s18, v6
	v_add_u32_e32 v9, s18, v7
	ds_read_b128 v[172:175], v9
	ds_read_b128 v[176:179], v9 offset:1024
	ds_read_b128 v[180:183], v9 offset:2048
	ds_read_b128 v[184:187], v9 offset:3072
	s_cmp_eq_u32 s15, 29
	s_cbranch_scc1 .Lg778_sw
.Lg778_swret:
	s_add_u32 m0, s16, s17
	s_setprio 1
	v_mfma_f32_16x16x32_bf16 v[132:135], v[192:195], v[10:13], v[132:135]
	v_mfma_f32_16x16x32_bf16 v[128:131], v[196:199], v[10:13], v[128:131]
	v_mfma_f32_16x16x32_bf16 v[124:127], v[200:203], v[10:13], v[124:127]
	v_mfma_f32_16x16x32_bf16 v[120:123], v[204:207], v[10:13], v[120:123]
	ds_read_b128 v[10:13], v8
	v_mfma_f32_16x16x32_bf16 v[100:103], v[192:195], v[14:17], v[100:103]
	v_mfma_f32_16x16x32_bf16 v[96:99], v[196:199], v[14:17], v[96:99]
	v_mfma_f32_16x16x32_bf16 v[92:95], v[200:203], v[14:17], v[92:95]
	v_mfma_f32_16x16x32_bf16 v[88:91], v[204:207], v[14:17], v[88:91]
	ds_read_b128 v[14:17], v8 offset:1024
	v_mfma_f32_16x16x32_bf16 v[68:71], v[192:195], v[18:21], v[68:71]
	global_load_lds_dwordx4 v0, s[98:99]
	v_mfma_f32_16x16x32_bf16 v[64:67], v[196:199], v[18:21], v[64:67]
	global_load_lds_dwordx4 v1, s[98:99] offset:1024
	v_mfma_f32_16x16x32_bf16 v[60:63], v[200:203], v[18:21], v[60:63]
	global_load_lds_dwordx4 v2, s[100:101] offset:2048
	v_mfma_f32_16x16x32_bf16 v[56:59], v[204:207], v[18:21], v[56:59]
	global_load_lds_dwordx4 v3, s[100:101] offset:3072
	ds_read_b128 v[18:21], v8 offset:6144
	v_mfma_f32_16x16x32_bf16 v[36:39], v[192:195], v[152:155], v[36:39]
	s_add_u32 m0, m0, 0x1000
	v_mfma_f32_16x16x32_bf16 v[32:35], v[196:199], v[152:155], v[32:35]
	global_load_lds_dwordx4 v4, s[100:101]
	v_mfma_f32_16x16x32_bf16 v[28:31], v[200:203], v[152:155], v[28:31]
	global_load_lds_dwordx4 v5, s[100:101] offset:1024
	v_mfma_f32_16x16x32_bf16 v[24:27], v[204:207], v[152:155], v[24:27]
	ds_read_b128 v[152:155], v8 offset:7168
	ds_read_b128 v[192:195], v9 offset:6144
	ds_read_b128 v[196:199], v9 offset:7168
	ds_read_b128 v[200:203], v9 offset:8192
	ds_read_b128 v[204:207], v9 offset:9216
	s_add_u32 s98, s98, 0x200000
	s_addc_u32 s99, s99, 0
	s_add_u32 s100, s100, 0x40000
	s_addc_u32 s101, s101, 0
	s_add_u32 s16, s16, 0x6000
	s_cmp_eq_u32 s16, 0x12000
	s_cselect_b32 s16, 0, s16
	s_add_u32 s15, s15, 1
	s_cmp_lt_u32 s15, 31
	s_cbranch_scc1 .Lg778_top
	s_setprio 0
	s_waitcnt lgkmcnt(4)
	v_mfma_f32_16x16x32_bf16 v[148:151], v[172:175], v[10:13], v[148:151]
	v_mfma_f32_16x16x32_bf16 v[116:119], v[172:175], v[14:17], v[116:119]
	v_mfma_f32_16x16x32_bf16 v[84:87], v[172:175], v[18:21], v[84:87]
	v_mfma_f32_16x16x32_bf16 v[52:55], v[172:175], v[152:155], v[52:55]
	v_mfma_f32_16x16x32_bf16 v[144:147], v[176:179], v[10:13], v[144:147]
	v_mfma_f32_16x16x32_bf16 v[112:115], v[176:179], v[14:17], v[112:115]
	v_mfma_f32_16x16x32_bf16 v[80:83], v[176:179], v[18:21], v[80:83]
	v_mfma_f32_16x16x32_bf16 v[48:51], v[176:179], v[152:155], v[48:51]
	v_mfma_f32_16x16x32_bf16 v[140:143], v[180:183], v[10:13], v[140:143]
	v_mfma_f32_16x16x32_bf16 v[108:111], v[180:183], v[14:17], v[108:111]
	v_mfma_f32_16x16x32_bf16 v[76:79], v[180:183], v[18:21], v[76:79]
	v_mfma_f32_16x16x32_bf16 v[44:47], v[180:183], v[152:155], v[44:47]
	v_mfma_f32_16x16x32_bf16 v[136:139], v[184:187], v[10:13], v[136:139]
	v_mfma_f32_16x16x32_bf16 v[104:107], v[184:187], v[14:17], v[104:107]
	v_mfma_f32_16x16x32_bf16 v[72:75], v[184:187], v[18:21], v[72:75]
	v_mfma_f32_16x16x32_bf16 v[40:43], v[184:187], v[152:155], v[40:43]
	s_waitcnt vmcnt(6)
	s_waitcnt lgkmcnt(0)
	s_barrier
	s_add_u32 m0, s16, s17
	s_setprio 1
	v_mfma_f32_16x16x32_bf16 v[132:135], v[192:195], v[10:13], v[132:135]
	v_mfma_f32_16x16x32_bf16 v[128:131], v[196:199], v[10:13], v[128:131]
	v_mfma_f32_16x16x32_bf16 v[124:127], v[200:203], v[10:13], v[124:127]
	v_mfma_f32_16x16x32_bf16 v[120:123], v[204:207], v[10:13], v[120:123]
	v_mfma_f32_16x16x32_bf16 v[100:103], v[192:195], v[14:17], v[100:103]
	v_mfma_f32_16x16x32_bf16 v[96:99], v[196:199], v[14:17], v[96:99]
	v_mfma_f32_16x16x32_bf16 v[92:95], v[200:203], v[14:17], v[92:95]
	v_mfma_f32_16x16x32_bf16 v[88:91], v[204:207], v[14:17], v[88:91]
	v_mfma_f32_16x16x32_bf16 v[68:71], v[192:195], v[18:21], v[68:71]
	global_load_lds_dwordx4 v0, s[98:99]
	v_mfma_f32_16x16x32_bf16 v[64:67], v[196:199], v[18:21], v[64:67]
	global_load_lds_dwordx4 v1, s[98:99] offset:1024
	v_mfma_f32_16x16x32_bf16 v[60:63], v[200:203], v[18:21], v[60:63]
	global_load_lds_dwordx4 v2, s[100:101] offset:2048
	v_mfma_f32_16x16x32_bf16 v[56:59], v[204:207], v[18:21], v[56:59]
	global_load_lds_dwordx4 v3, s[100:101] offset:3072
	v_mfma_f32_16x16x32_bf16 v[36:39], v[192:195], v[152:155], v[36:39]
	s_add_u32 m0, m0, 0x1000
	v_mfma_f32_16x16x32_bf16 v[32:35], v[196:199], v[152:155], v[32:35]
	global_load_lds_dwordx4 v4, s[100:101]
	v_mfma_f32_16x16x32_bf16 v[28:31], v[200:203], v[152:155], v[28:31]
	global_load_lds_dwordx4 v5, s[100:101] offset:1024
	v_mfma_f32_16x16x32_bf16 v[24:27], v[204:207], v[152:155], v[24:27]
	s_add_u32 s98, s98, 0x200000
	s_addc_u32 s99, s99, 0
	s_add_u32 s100, s100, 0x40000
	s_addc_u32 s101, s101, 0
	s_add_u32 s16, s16, 0x6000
	s_cmp_eq_u32 s16, 0x12000
	s_cselect_b32 s16, 0, s16
	s_add_u32 s15, s15, 1
	s_branch .Lg778_end

; DI f32x4 mfma(bf16x8 a, bf16x8 b, f32x4 c) { return __builtin_amdgcn_mfma_f32_16x16x32_bf16(a, b, c, 0, 0, 0); }
; #define G_LOAD(PA, PB, STEP) do { _Pragma("unroll") for (int i_ = 0; i_ < 2; ++i_) ra[i_] = *(const u32x4*)((PA) + (size_t)(64 * i_) * K + (STEP) * 32); \
;         _Pragma("unroll") for (int i_ = 0; i_ < 4; ++i_) rb[i_] = *(const u32x4*)((PB) + (size_t)(64 * i_) * K + (STEP) * 32); } while (0)
; #define G_STORE(BUF) do { _Pragma("unroll") for (int i_ = 0; i_ < 2; ++i_) *(u32x4*)(sA + (BUF) * 128 * 40 + (lrow + 64 * i_) * 40 + lcc * 8) = ra[i_]; \
;         _Pragma("unroll") for (int i_ = 0; i_ < 4; ++i_) *(u32x4*)(sB + (BUF) * 256 * 40 + (lrow + 64 * i_) * 40 + lcc * 8) = rb[i_]; } while (0)
; template <int EPI> ...
;     ...
;         for (int kt = 0; kt < nk; ++kt) {
;             const int buf = kt & 1;
;             const bf16_t* a_ = sA + buf * 128 * 40 + (wr * 64 + fr) * 40 + fq * 8;
;             const bf16_t* b_ = sB + buf * 256 * 40 + (wc * 128 + fr) * 40 + fq * 8;
;             bf16x8 af[4];
; #pragma unroll
;             for (int i = 0; i < 4; ++i) af[i] = *(const bf16x8*)(a_ + i * 16 * 40);
; #pragma unroll
;             for (int jh = 0; jh < 2; ++jh) {
;                 bf16x8 bfr[4];
; #pragma unroll
;                 for (int j = 0; j < 4; ++j) bfr[j] = *(const bf16x8*)(b_ + (jh * 4 + j) * 16 * 40);
; #pragma unroll
;                 for (int i = 0; i < 4; ++i)
; #pragma unroll
;                     for (int j = 0; j < 4; ++j) acc[i][jh * 4 + j] = mfma(bfr[j], af[i], acc[i][jh * 4 + j]);
;             }
;             G_STORE(buf ^ 1);
;             {
;                 const bool cur = kt + 2 < nk;
;                 const bf16_t* pa = cur ? Ag : An; const bf16_t* pb = cur ? Bg : Bn;
;                 const int st = cur ? kt + 2 : kt + 2 - nk;
;                 G_LOAD(pa, pb, st);
;             }
;             __syncthreads();
;         }
.Lg843_top:
	s_setprio 0
	s_waitcnt lgkmcnt(4)
	v_mfma_f32_16x16x32_bf16 v[148:151], v[174:177], v[10:13], v[148:151]
	v_mfma_f32_16x16x32_bf16 v[116:119], v[174:177], v[14:17], v[116:119]
	v_mfma_f32_16x16x32_bf16 v[84:87], v[174:177], v[18:21], v[84:87]
	v_mfma_f32_16x16x32_bf16 v[52:55], v[174:177], v[154:157], v[52:55]
	v_mfma_f32_16x16x32_bf16 v[144:147], v[178:181], v[10:13], v[144:147]
	v_mfma_f32_16x16x32_bf16 v[112:115], v[178:181], v[14:17], v[112:115]
	v_mfma_f32_16x16x32_bf16 v[80:83], v[178:181], v[18:21], v[80:83]
	v_mfma_f32_16x16x32_bf16 v[48:51], v[178:181], v[154:157], v[48:51]
	v_mfma_f32_16x16x32_bf16 v[140:143], v[182:185], v[10:13], v[140:143]
	v_mfma_f32_16x16x32_bf16 v[108:111], v[182:185], v[14:17], v[108:111]
	v_mfma_f32_16x16x32_bf16 v[76:79], v[182:185], v[18:21], v[76:79]
	v_mfma_f32_16x16x32_bf16 v[44:47], v[182:185], v[154:157], v[44:47]
	v_mfma_f32_16x16x32_bf16 v[136:139], v[192:195], v[10:13], v[136:139]
	v_mfma_f32_16x16x32_bf16 v[104:107], v[192:195], v[14:17], v[104:107]
	v_mfma_f32_16x16x32_bf16 v[72:75], v[192:195], v[18:21], v[72:75]
	v_mfma_f32_16x16x32_bf16 v[40:43], v[192:195], v[154:157], v[40:43]
	s_waitcnt vmcnt(6)
	s_waitcnt lgkmcnt(0)
	s_barrier
	s_add_u32 s17, s15, 0x6000
	s_cmp_eq_u32 s17, 0x12000
	s_cselect_b32 s17, 0, s17
	v_add_u32_e32 v8, s17, v6
	v_add_u32_e32 v9, s17, v7
	ds_read_b128 v[174:177], v9
	ds_read_b128 v[178:181], v9 offset:1024
	ds_read_b128 v[182:185], v9 offset:2048
	ds_read_b128 v[192:195], v9 offset:3072
	s_cmp_eq_u32 s14, 125
	s_cbranch_scc1 .Lg843_sw
.Lg843_swret:
	s_add_u32 m0, s15, s16
	s_setprio 1
	v_mfma_f32_16x16x32_bf16 v[132:135], v[196:199], v[10:13], v[132:135]
	v_mfma_f32_16x16x32_bf16 v[128:131], v[200:203], v[10:13], v[128:131]
	v_mfma_f32_16x16x32_bf16 v[124:127], v[204:207], v[10:13], v[124:127]
	v_mfma_f32_16x16x32_bf16 v[120:123], v[232:235], v[10:13], v[120:123]
	ds_read_b128 v[10:13], v8
	v_mfma_f32_16x16x32_bf16 v[100:103], v[196:199], v[14:17], v[100:103]
	v_mfma_f32_16x16x32_bf16 v[96:99], v[200:203], v[14:17], v[96:99]
	v_mfma_f32_16x16x32_bf16 v[92:95], v[204:207], v[14:17], v[92:95]
	v_mfma_f32_16x16x32_bf16 v[88:91], v[232:235], v[14:17], v[88:91]
	ds_read_b128 v[14:17], v8 offset:1024
	v_mfma_f32_16x16x32_bf16 v[68:71], v[196:199], v[18:21], v[68:71]
	global_load_lds_dwordx4 v0, s[98:99]
	v_mfma_f32_16x16x32_bf16 v[64:67], v[200:203], v[18:21], v[64:67]
	global_load_lds_dwordx4 v1, s[98:99] offset:1024
	v_mfma_f32_16x16x32_bf16 v[60:63], v[204:207], v[18:21], v[60:63]
	global_load_lds_dwordx4 v2, s[100:101] offset:2048
	v_mfma_f32_16x16x32_bf16 v[56:59], v[232:235], v[18:21], v[56:59]
	global_load_lds_dwordx4 v3, s[100:101] offset:3072
	ds_read_b128 v[18:21], v8 offset:6144
	v_mfma_f32_16x16x32_bf16 v[36:39], v[196:199], v[154:157], v[36:39]
	s_add_u32 m0, m0, 0x1000
	v_mfma_f32_16x16x32_bf16 v[32:35], v[200:203], v[154:157], v[32:35]
	global_load_lds_dwordx4 v4, s[100:101]
	v_mfma_f32_16x16x32_bf16 v[28:31], v[204:207], v[154:157], v[28:31]
	global_load_lds_dwordx4 v5, s[100:101] offset:1024
	v_mfma_f32_16x16x32_bf16 v[24:27], v[232:235], v[154:157], v[24:27]
	ds_read_b128 v[154:157], v8 offset:7168
	ds_read_b128 v[196:199], v9 offset:6144
	ds_read_b128 v[200:203], v9 offset:7168
	ds_read_b128 v[204:207], v9 offset:8192
	ds_read_b128 v[232:235], v9 offset:9216
	s_add_u32 s98, s98, 0x200000
	s_addc_u32 s99, s99, 0
	s_add_u32 s100, s100, 0x10000
	s_addc_u32 s101, s101, 0
	s_add_u32 s15, s15, 0x6000
	s_cmp_eq_u32 s15, 0x12000
	s_cselect_b32 s15, 0, s15
	s_add_u32 s14, s14, 1
	s_cmp_lt_u32 s14, 127
	s_cbranch_scc1 .Lg843_top
	s_setprio 0
	s_waitcnt lgkmcnt(4)
	v_mfma_f32_16x16x32_bf16 v[148:151], v[174:177], v[10:13], v[148:151]
	v_mfma_f32_16x16x32_bf16 v[116:119], v[174:177], v[14:17], v[116:119]
	v_mfma_f32_16x16x32_bf16 v[84:87], v[174:177], v[18:21], v[84:87]
	v_mfma_f32_16x16x32_bf16 v[52:55], v[174:177], v[154:157], v[52:55]
	v_mfma_f32_16x16x32_bf16 v[144:147], v[178:181], v[10:13], v[144:147]
	v_mfma_f32_16x16x32_bf16 v[112:115], v[178:181], v[14:17], v[112:115]
	v_mfma_f32_16x16x32_bf16 v[80:83], v[178:181], v[18:21], v[80:83]
	v_mfma_f32_16x16x32_bf16 v[48:51], v[178:181], v[154:157], v[48:51]
	v_mfma_f32_16x16x32_bf16 v[140:143], v[182:185], v[10:13], v[140:143]
	v_mfma_f32_16x16x32_bf16 v[108:111], v[182:185], v[14:17], v[108:111]
	v_mfma_f32_16x16x32_bf16 v[76:79], v[182:185], v[18:21], v[76:79]
	v_mfma_f32_16x16x32_bf16 v[44:47], v[182:185], v[154:157], v[44:47]
	v_mfma_f32_16x16x32_bf16 v[136:139], v[192:195], v[10:13], v[136:139]
	v_mfma_f32_16x16x32_bf16 v[104:107], v[192:195], v[14:17], v[104:107]
	v_mfma_f32_16x16x32_bf16 v[72:75], v[192:195], v[18:21], v[72:75]
	v_mfma_f32_16x16x32_bf16 v[40:43], v[192:195], v[154:157], v[40:43]
	s_waitcnt vmcnt(6)
	s_waitcnt lgkmcnt(0)
	s_barrier
	s_add_u32 m0, s15, s16
	s_setprio 1
	v_mfma_f32_16x16x32_bf16 v[132:135], v[196:199], v[10:13], v[132:135]
	v_mfma_f32_16x16x32_bf16 v[128:131], v[200:203], v[10:13], v[128:131]
	v_mfma_f32_16x16x32_bf16 v[124:127], v[204:207], v[10:13], v[124:127]
	v_mfma_f32_16x16x32_bf16 v[120:123], v[232:235], v[10:13], v[120:123]
	v_mfma_f32_16x16x32_bf16 v[100:103], v[196:199], v[14:17], v[100:103]
	v_mfma_f32_16x16x32_bf16 v[96:99], v[200:203], v[14:17], v[96:99]
	v_mfma_f32_16x16x32_bf16 v[92:95], v[204:207], v[14:17], v[92:95]
	v_mfma_f32_16x16x32_bf16 v[88:91], v[232:235], v[14:17], v[88:91]
	v_mfma_f32_16x16x32_bf16 v[68:71], v[196:199], v[18:21], v[68:71]
	global_load_lds_dwordx4 v0, s[98:99]
	v_mfma_f32_16x16x32_bf16 v[64:67], v[200:203], v[18:21], v[64:67]
	global_load_lds_dwordx4 v1, s[98:99] offset:1024
	v_mfma_f32_16x16x32_bf16 v[60:63], v[204:207], v[18:21], v[60:63]
	global_load_lds_dwordx4 v2, s[100:101] offset:2048
	v_mfma_f32_16x16x32_bf16 v[56:59], v[232:235], v[18:21], v[56:59]
	global_load_lds_dwordx4 v3, s[100:101] offset:3072
	v_mfma_f32_16x16x32_bf16 v[36:39], v[196:199], v[154:157], v[36:39]
	s_add_u32 m0, m0, 0x1000
	v_mfma_f32_16x16x32_bf16 v[32:35], v[200:203], v[154:157], v[32:35]
	global_load_lds_dwordx4 v4, s[100:101]
	v_mfma_f32_16x16x32_bf16 v[28:31], v[204:207], v[154:157], v[28:31]
	global_load_lds_dwordx4 v5, s[100:101] offset:1024
	v_mfma_f32_16x16x32_bf16 v[24:27], v[232:235], v[154:157], v[24:27]
	s_add_u32 s98, s98, 0x200000
	s_addc_u32 s99, s99, 0
	s_add_u32 s100, s100, 0x10000
	s_addc_u32 s101, s101, 0
	s_add_u32 s15, s15, 0x6000
	s_cmp_eq_u32 s15, 0x12000
	s_cselect_b32 s15, 0, s15
	s_add_u32 s14, s14, 1
	s_branch .Lg843_end

; DI f32x4 mfma(bf16x8 a, bf16x8 b, f32x4 c) { return __builtin_amdgcn_mfma_f32_16x16x32_bf16(a, b, c, 0, 0, 0); }
; #define G_LOAD(PA, PB, STEP) do { _Pragma("unroll") for (int i_ = 0; i_ < 2; ++i_) ra[i_] = *(const u32x4*)((PA) + (size_t)(64 * i_) * K + (STEP) * 32); \
;         _Pragma("unroll") for (int i_ = 0; i_ < 4; ++i_) rb[i_] = *(const u32x4*)((PB) + (size_t)(64 * i_) * K + (STEP) * 32); } while (0)
; #define G_STORE(BUF) do { _Pragma("unroll") for (int i_ = 0; i_ < 2; ++i_) *(u32x4*)(sA + (BUF) * 128 * 40 + (lrow + 64 * i_) * 40 + lcc * 8) = ra[i_]; \
;         _Pragma("unroll") for (int i_ = 0; i_ < 4; ++i_) *(u32x4*)(sB + (BUF) * 256 * 40 + (lrow + 64 * i_) * 40 + lcc * 8) = rb[i_]; } while (0)
; template <int EPI> ...
;     ...
;         for (int kt = 0; kt < nk; ++kt) {
;             const int buf = kt & 1;
;             const bf16_t* a_ = sA + buf * 128 * 40 + (wr * 64 + fr) * 40 + fq * 8;
;             const bf16_t* b_ = sB + buf * 256 * 40 + (wc * 128 + fr) * 40 + fq * 8;
;             bf16x8 af[4];
; #pragma unroll
;             for (int i = 0; i < 4; ++i) af[i] = *(const bf16x8*)(a_ + i * 16 * 40);
; #pragma unroll
;             for (int jh = 0; jh < 2; ++jh) {
;                 bf16x8 bfr[4];
; #pragma unroll
;                 for (int j = 0; j < 4; ++j) bfr[j] = *(const bf16x8*)(b_ + (jh * 4 + j) * 16 * 40);
; #pragma unroll
;                 for (int i = 0; i < 4; ++i)
; #pragma unroll
;                     for (int j = 0; j < 4; ++j) acc[i][jh * 4 + j] = mfma(bfr[j], af[i], acc[i][jh * 4 + j]);
;             }
;             G_STORE(buf ^ 1);
;             {
;                 const bool cur = kt + 2 < nk;
;                 const bf16_t* pa = cur ? Ag : An; const bf16_t* pb = cur ? Bg : Bn;
;                 const int st = cur ? kt + 2 : kt + 2 - nk;
;                 G_LOAD(pa, pb, st);
;             }
;             __syncthreads();
;         }
.Lg853_top:
	s_setprio 0
	s_waitcnt lgkmcnt(4)
	v_mfma_f32_16x16x32_bf16 v[148:151], v[174:177], v[10:13], v[148:151]
	v_mfma_f32_16x16x32_bf16 v[116:119], v[174:177], v[14:17], v[116:119]
	v_mfma_f32_16x16x32_bf16 v[84:87], v[174:177], v[18:21], v[84:87]
	v_mfma_f32_16x16x32_bf16 v[52:55], v[174:177], v[154:157], v[52:55]
	v_mfma_f32_16x16x32_bf16 v[144:147], v[192:195], v[10:13], v[144:147]
	v_mfma_f32_16x16x32_bf16 v[112:115], v[192:195], v[14:17], v[112:115]
	v_mfma_f32_16x16x32_bf16 v[80:83], v[192:195], v[18:21], v[80:83]
	v_mfma_f32_16x16x32_bf16 v[48:51], v[192:195], v[154:157], v[48:51]
	v_mfma_f32_16x16x32_bf16 v[140:143], v[196:199], v[10:13], v[140:143]
	v_mfma_f32_16x16x32_bf16 v[108:111], v[196:199], v[14:17], v[108:111]
	v_mfma_f32_16x16x32_bf16 v[76:79], v[196:199], v[18:21], v[76:79]
	v_mfma_f32_16x16x32_bf16 v[44:47], v[196:199], v[154:157], v[44:47]
	v_mfma_f32_16x16x32_bf16 v[136:139], v[200:203], v[10:13], v[136:139]
	v_mfma_f32_16x16x32_bf16 v[104:107], v[200:203], v[14:17], v[104:107]
	v_mfma_f32_16x16x32_bf16 v[72:75], v[200:203], v[18:21], v[72:75]
	v_mfma_f32_16x16x32_bf16 v[40:43], v[200:203], v[154:157], v[40:43]
	s_waitcnt vmcnt(6)
	s_waitcnt lgkmcnt(0)
	s_barrier
	s_add_u32 s17, s15, 0x6000
	s_cmp_eq_u32 s17, 0x12000
	s_cselect_b32 s17, 0, s17
	v_add_u32_e32 v8, s17, v6
	v_add_u32_e32 v9, s17, v7
	ds_read_b128 v[174:177], v9
	ds_read_b128 v[192:195], v9 offset:1024
	ds_read_b128 v[196:199], v9 offset:2048
	ds_read_b128 v[200:203], v9 offset:3072
	s_cmp_eq_u32 s14, 125
	s_cbranch_scc1 .Lg853_sw
.Lg853_swret:
	s_add_u32 m0, s15, s16
	s_setprio 1
	v_mfma_f32_16x16x32_bf16 v[132:135], v[204:207], v[10:13], v[132:135]
	v_mfma_f32_16x16x32_bf16 v[128:131], v[232:235], v[10:13], v[128:131]
	v_mfma_f32_16x16x32_bf16 v[124:127], v[236:239], v[10:13], v[124:127]
	v_mfma_f32_16x16x32_bf16 v[120:123], v[240:243], v[10:13], v[120:123]
	ds_read_b128 v[10:13], v8
	v_mfma_f32_16x16x32_bf16 v[100:103], v[204:207], v[14:17], v[100:103]
	v_mfma_f32_16x16x32_bf16 v[96:99], v[232:235], v[14:17], v[96:99]
	v_mfma_f32_16x16x32_bf16 v[92:95], v[236:239], v[14:17], v[92:95]
	v_mfma_f32_16x16x32_bf16 v[88:91], v[240:243], v[14:17], v[88:91]
	ds_read_b128 v[14:17], v8 offset:1024
	v_mfma_f32_16x16x32_bf16 v[68:71], v[204:207], v[18:21], v[68:71]
	global_load_lds_dwordx4 v0, s[98:99]
	v_mfma_f32_16x16x32_bf16 v[64:67], v[232:235], v[18:21], v[64:67]
	global_load_lds_dwordx4 v1, s[98:99] offset:1024
	v_mfma_f32_16x16x32_bf16 v[60:63], v[236:239], v[18:21], v[60:63]
	global_load_lds_dwordx4 v2, s[100:101] offset:2048
	v_mfma_f32_16x16x32_bf16 v[56:59], v[240:243], v[18:21], v[56:59]
	global_load_lds_dwordx4 v3, s[100:101] offset:3072
	ds_read_b128 v[18:21], v8 offset:6144
	v_mfma_f32_16x16x32_bf16 v[36:39], v[204:207], v[154:157], v[36:39]
	s_add_u32 m0, m0, 0x1000
	v_mfma_f32_16x16x32_bf16 v[32:35], v[232:235], v[154:157], v[32:35]
	global_load_lds_dwordx4 v4, s[100:101]
	v_mfma_f32_16x16x32_bf16 v[28:31], v[236:239], v[154:157], v[28:31]
	global_load_lds_dwordx4 v5, s[100:101] offset:1024
	v_mfma_f32_16x16x32_bf16 v[24:27], v[240:243], v[154:157], v[24:27]
	ds_read_b128 v[154:157], v8 offset:7168
	ds_read_b128 v[204:207], v9 offset:6144
	ds_read_b128 v[232:235], v9 offset:7168
	ds_read_b128 v[236:239], v9 offset:8192
	ds_read_b128 v[240:243], v9 offset:9216
	s_add_u32 s98, s98, 0x200000
	s_addc_u32 s99, s99, 0
	s_add_u32 s100, s100, 0x10000
	s_addc_u32 s101, s101, 0
	s_add_u32 s15, s15, 0x6000
	s_cmp_eq_u32 s15, 0x12000
	s_cselect_b32 s15, 0, s15
	s_add_u32 s14, s14, 1
	s_cmp_lt_u32 s14, 127
	s_cbranch_scc1 .Lg853_top
	s_setprio 0
	s_waitcnt lgkmcnt(4)
	v_mfma_f32_16x16x32_bf16 v[148:151], v[174:177], v[10:13], v[148:151]
	v_mfma_f32_16x16x32_bf16 v[116:119], v[174:177], v[14:17], v[116:119]
	v_mfma_f32_16x16x32_bf16 v[84:87], v[174:177], v[18:21], v[84:87]
	v_mfma_f32_16x16x32_bf16 v[52:55], v[174:177], v[154:157], v[52:55]
	v_mfma_f32_16x16x32_bf16 v[144:147], v[192:195], v[10:13], v[144:147]
	v_mfma_f32_16x16x32_bf16 v[112:115], v[192:195], v[14:17], v[112:115]
	v_mfma_f32_16x16x32_bf16 v[80:83], v[192:195], v[18:21], v[80:83]
	v_mfma_f32_16x16x32_bf16 v[48:51], v[192:195], v[154:157], v[48:51]
	v_mfma_f32_16x16x32_bf16 v[140:143], v[196:199], v[10:13], v[140:143]
	v_mfma_f32_16x16x32_bf16 v[108:111], v[196:199], v[14:17], v[108:111]
	v_mfma_f32_16x16x32_bf16 v[76:79], v[196:199], v[18:21], v[76:79]
	v_mfma_f32_16x16x32_bf16 v[44:47], v[196:199], v[154:157], v[44:47]
	v_mfma_f32_16x16x32_bf16 v[136:139], v[200:203], v[10:13], v[136:139]
	v_mfma_f32_16x16x32_bf16 v[104:107], v[200:203], v[14:17], v[104:107]
	v_mfma_f32_16x16x32_bf16 v[72:75], v[200:203], v[18:21], v[72:75]
	v_mfma_f32_16x16x32_bf16 v[40:43], v[200:203], v[154:157], v[40:43]
	s_waitcnt vmcnt(6)
	s_waitcnt lgkmcnt(0)
	s_barrier
	s_add_u32 m0, s15, s16
	s_setprio 1
	v_mfma_f32_16x16x32_bf16 v[132:135], v[204:207], v[10:13], v[132:135]
	v_mfma_f32_16x16x32_bf16 v[128:131], v[232:235], v[10:13], v[128:131]
	v_mfma_f32_16x16x32_bf16 v[124:127], v[236:239], v[10:13], v[124:127]
	v_mfma_f32_16x16x32_bf16 v[120:123], v[240:243], v[10:13], v[120:123]
	v_mfma_f32_16x16x32_bf16 v[100:103], v[204:207], v[14:17], v[100:103]
	v_mfma_f32_16x16x32_bf16 v[96:99], v[232:235], v[14:17], v[96:99]
	v_mfma_f32_16x16x32_bf16 v[92:95], v[236:239], v[14:17], v[92:95]
	v_mfma_f32_16x16x32_bf16 v[88:91], v[240:243], v[14:17], v[88:91]
	v_mfma_f32_16x16x32_bf16 v[68:71], v[204:207], v[18:21], v[68:71]
	global_load_lds_dwordx4 v0, s[98:99]
	v_mfma_f32_16x16x32_bf16 v[64:67], v[232:235], v[18:21], v[64:67]
	global_load_lds_dwordx4 v1, s[98:99] offset:1024
	v_mfma_f32_16x16x32_bf16 v[60:63], v[236:239], v[18:21], v[60:63]
	global_load_lds_dwordx4 v2, s[100:101] offset:2048
	v_mfma_f32_16x16x32_bf16 v[56:59], v[240:243], v[18:21], v[56:59]
	global_load_lds_dwordx4 v3, s[100:101] offset:3072
	v_mfma_f32_16x16x32_bf16 v[36:39], v[204:207], v[154:157], v[36:39]
	s_add_u32 m0, m0, 0x1000
	v_mfma_f32_16x16x32_bf16 v[32:35], v[232:235], v[154:157], v[32:35]
	global_load_lds_dwordx4 v4, s[100:101]
	v_mfma_f32_16x16x32_bf16 v[28:31], v[236:239], v[154:157], v[28:31]
	global_load_lds_dwordx4 v5, s[100:101] offset:1024
	v_mfma_f32_16x16x32_bf16 v[24:27], v[240:243], v[154:157], v[24:27]
	s_add_u32 s98, s98, 0x200000
	s_addc_u32 s99, s99, 0
	s_add_u32 s100, s100, 0x10000
	s_addc_u32 s101, s101, 0
	s_add_u32 s15, s15, 0x6000
	s_cmp_eq_u32 s15, 0x12000
	s_cselect_b32 s15, 0, s15
	s_add_u32 s14, s14, 1
	s_branch .Lg853_end
